# GU phases: second-half ssq partial loads hoisted to the epilogue start (overlap with first-half SwiGLU math)
# speedup vs baseline: 1.0243x; 1.0059x over previous
.LBB0_164:
	s_lshl_b32 s11, s18, 8
	v_add_u32_e32 v146, s11, v149
	v_or_b32_e32 v162, 16, v146
	v_ashrrev_i32_e32 v147, 31, v146
	v_ashrrev_i32_e32 v163, 31, v162
	v_lshlrev_b64 v[160:161], 6, v[146:147]
	v_lshlrev_b64 v[162:163], 6, v[162:163]
	v_lshl_add_u64 v[160:161], v[136:137], 0, v[160:161]
	v_lshl_add_u64 v[166:167], v[136:137], 0, v[162:163]
	v_mov_b32_e32 v162, v236
	v_mov_b32_e32 v163, v237
	v_mov_b32_e32 v164, v238
	v_mov_b32_e32 v165, v239
	v_mov_b32_e32 v166, v240
	v_mov_b32_e32 v167, v241
	v_mov_b32_e32 v168, v242
	v_mov_b32_e32 v169, v243
	v_or_b32_e32 v160, 32, v146
	v_ashrrev_i32_e32 v161, 31, v160
	v_lshlrev_b64 v[160:161], 6, v[160:161]
	v_lshl_add_u64 v[160:161], v[136:137], 0, v[160:161]
	v_mov_b32_e32 v170, v244
	v_mov_b32_e32 v171, v245
	v_mov_b32_e32 v172, v246
	v_mov_b32_e32 v173, v247
	v_or_b32_e32 v160, 48, v146
	v_ashrrev_i32_e32 v161, 31, v160
	v_lshlrev_b64 v[160:161], 6, v[160:161]
	v_lshl_add_u64 v[160:161], v[136:137], 0, v[160:161]
	v_mov_b32_e32 v174, v248
	v_mov_b32_e32 v175, v249
	v_mov_b32_e32 v176, v250
	v_mov_b32_e32 v177, v251
	v_add_u32_e32 v252, 0x80, v146
	v_mov_b32_e32 v253, 0
	v_lshlrev_b64 v[252:253], 6, v[252:253]
	v_lshl_add_u64 v[252:253], v[136:137], 0, v[252:253]
	global_load_dwordx4 v[236:239], v[252:253], off
	global_load_dwordx4 v[240:243], v[252:253], off offset:1024
	global_load_dwordx4 v[244:247], v[252:253], off offset:2048
	global_load_dwordx4 v[248:251], v[252:253], off offset:3072
	v_and_b32_e32 v148, 64, v158
	v_xor_b32_e32 v147, 16, v158
	v_add_u32_e32 v148, 64, v148
	v_xor_b32_e32 v160, 32, v158
	v_cmp_lt_i32_e32 vcc, v147, v148
	v_lshl_or_b32 v178, s49, 7, v154
	v_ashrrev_i32_e32 v179, 31, v178
	v_cndmask_b32_e32 v147, v158, v147, vcc
	v_cmp_lt_i32_e32 vcc, v160, v148
	v_mov_b32_e32 v180, v163
	v_mov_b32_e32 v181, v164
	v_mov_b32_e32 v163, v165
	v_cndmask_b32_e32 v148, v158, v160, vcc
	v_pk_add_f32 v[162:163], v[180:181], v[162:163]
	v_lshlrev_b32_e32 v160, 2, v147
	v_lshlrev_b32_e32 v147, 2, v148
	v_mov_b32_e32 v164, v167
	v_mov_b32_e32 v165, v168
	v_mov_b32_e32 v167, v169
	v_add_f32_e32 v148, v162, v163
	v_mov_b32_e32 v168, v171
	v_mov_b32_e32 v169, v172
	v_mov_b32_e32 v171, v173
	v_pk_add_f32 v[162:163], v[164:165], v[166:167]
	ds_bpermute_b32 v161, v160, v148
	v_mov_b32_e32 v172, v175
	v_mov_b32_e32 v173, v176
	v_mov_b32_e32 v175, v177
	v_pk_add_f32 v[164:165], v[168:169], v[170:171]
	v_add_f32_e32 v162, v162, v163
	v_pk_add_f32 v[166:167], v[172:173], v[174:175]
	v_add_f32_e32 v163, v164, v165
	ds_bpermute_b32 v165, v160, v162
	v_add_f32_e32 v164, v166, v167
	ds_bpermute_b32 v166, v160, v163
	ds_bpermute_b32 v167, v160, v164
	s_waitcnt lgkmcnt(3)
	v_add_f32_e32 v148, v148, v161
	ds_bpermute_b32 v161, v147, v148
	s_waitcnt lgkmcnt(3)
	v_add_f32_e32 v162, v162, v165
	ds_bpermute_b32 v165, v147, v162
	s_waitcnt lgkmcnt(3)
	v_add_f32_e32 v163, v163, v166
	s_waitcnt lgkmcnt(2)
	v_add_f32_e32 v164, v164, v167
	ds_bpermute_b32 v166, v147, v163
	ds_bpermute_b32 v167, v147, v164
	s_waitcnt lgkmcnt(3)
	v_add_f32_e32 v148, v148, v161
	v_fmamk_f32 v148, v148, 0x3a800000, v159
	s_waitcnt lgkmcnt(2)
	v_add_f32_e32 v161, v162, v165
	v_rsq_f32_e32 v162, v148
	s_waitcnt lgkmcnt(1)
	v_add_f32_e32 v163, v163, v166
	s_waitcnt lgkmcnt(0)
	v_add_f32_e32 v164, v164, v167
	v_fmamk_f32 v148, v161, 0x3a800000, v159
	v_fmamk_f32 v161, v163, 0x3a800000, v159
	v_fmamk_f32 v163, v164, 0x3a800000, v159
	v_pk_mul_f32 v[126:127], v[126:127], v[162:163] op_sel_hi:[1,0]
	v_pk_mul_f32 v[124:125], v[124:125], v[162:163] op_sel_hi:[1,0]
	v_pk_mul_f32 v[118:119], v[118:119], v[162:163] op_sel_hi:[1,0]
	v_pk_mul_f32 v[116:117], v[116:117], v[162:163] op_sel_hi:[1,0]
	v_mul_f32_e32 v118, v126, v118
	v_mul_f32_e32 v116, v124, v116
	v_mul_f32_e32 v124, 0xbfb8aa3b, v124
	v_mul_f32_e32 v117, v125, v117
	v_mul_f32_e32 v125, 0xbfb8aa3b, v125
	v_mul_f32_e32 v126, 0xbfb8aa3b, v126
	v_mul_f32_e32 v119, v127, v119
	v_mul_f32_e32 v127, 0xbfb8aa3b, v127
	v_exp_f32_e32 v124, v124
	v_exp_f32_e32 v125, v125
	v_exp_f32_e32 v126, v126
	v_exp_f32_e32 v127, v127
	v_pk_mul_f32 v[120:121], v[120:121], v[162:163] op_sel_hi:[1,0]
	v_pk_mul_f32 v[122:123], v[122:123], v[162:163] op_sel_hi:[1,0]
	v_pk_mul_f32 v[114:115], v[114:115], v[162:163] op_sel_hi:[1,0]
	v_pk_mul_f32 v[112:113], v[112:113], v[162:163] op_sel_hi:[1,0]
	v_mul_f32_e32 v162, 0xbfb8aa3b, v121
	v_add_f32_e32 v124, 1.0, v124
	v_add_f32_e32 v125, 1.0, v125
	v_add_f32_e32 v126, 1.0, v126
	v_exp_f32_e32 v162, v162
	v_add_f32_e32 v127, 1.0, v127
	v_rcp_f32_e32 v124, v124
	v_rcp_f32_e32 v125, v125
	v_rcp_f32_e32 v126, v126
	v_rcp_f32_e32 v127, v127
	v_rsq_f32_e32 v166, v161
	v_mul_f32_e32 v161, 0xbfb8aa3b, v120
	v_exp_f32_e32 v161, v161
	v_add_f32_e32 v162, 1.0, v162
	v_mul_f32_e32 v116, v116, v124
	v_mul_f32_e32 v117, v117, v125
	v_mul_f32_e32 v118, v118, v126
	v_mul_f32_e32 v119, v119, v127
	v_cvt_pk_bf16_f32 v116, v116, v117
	v_cvt_pk_bf16_f32 v117, v118, v119
	v_rcp_f32_e32 v118, v162
	v_add_f32_e32 v161, 1.0, v161
	v_mul_f32_e32 v113, v121, v113
	v_rcp_f32_e32 v161, v161
	v_mul_f32_e32 v113, v113, v118
	v_mul_f32_e32 v118, 0xbfb8aa3b, v122
	v_exp_f32_e32 v119, v118
	v_mul_f32_e32 v118, 0xbfb8aa3b, v123
	v_mul_f32_e32 v112, v120, v112
	v_exp_f32_e32 v120, v118
	v_mul_f32_e32 v112, v112, v161
	v_cvt_pk_bf16_f32 v118, v112, v113
	v_add_f32_e32 v112, 1.0, v119
	v_rcp_f32_e32 v112, v112
	v_add_f32_e32 v113, 1.0, v120
	v_rcp_f32_e32 v113, v113
	v_mul_f32_e32 v114, v122, v114
	v_rsq_f32_e32 v164, v148
	v_mul_f32_e32 v112, v114, v112
	v_mul_f32_e32 v114, v123, v115
	v_mul_f32_e32 v113, v114, v113
	v_cvt_pk_bf16_f32 v119, v112, v113
	v_mov_b64_e32 v[112:113], s[36:37]
	v_mad_i64_i32 v[120:121], s[22:23], v146, s48, v[112:113]
	v_lshlrev_b64 v[114:115], 1, v[178:179]
	v_lshl_add_u64 v[120:121], v[120:121], 0, v[114:115]
	v_pk_mul_f32 v[108:109], v[108:109], v[164:165] op_sel_hi:[1,0]
	global_store_dwordx4 v[120:121], v[116:119], off
	v_pk_mul_f32 v[100:101], v[100:101], v[164:165] op_sel_hi:[1,0]
	v_pk_mul_f32 v[110:111], v[110:111], v[164:165] op_sel_hi:[1,0]
	v_pk_mul_f32 v[116:117], v[98:99], v[164:165] op_sel_hi:[1,0]
	v_mul_f32_e32 v98, 0xbfb8aa3b, v108
	v_exp_f32_e32 v119, v98
	v_mul_f32_e32 v98, 0xbfb8aa3b, v109
	v_exp_f32_e32 v120, v98
	v_pk_mul_f32 v[98:99], v[96:97], v[164:165] op_sel_hi:[1,0]
	v_add_f32_e32 v96, 1.0, v119
	v_rcp_f32_e32 v96, v96
	v_add_f32_e32 v97, 1.0, v120
	v_rcp_f32_e32 v97, v97
	v_mul_f32_e32 v100, v108, v100
	v_mul_f32_e32 v96, v100, v96
	v_mul_f32_e32 v100, v109, v101
	v_mul_f32_e32 v97, v100, v97
	v_mul_f32_e32 v100, 0xbfb8aa3b, v110
	v_exp_f32_e32 v100, v100
	v_mul_f32_e32 v101, 0xbfb8aa3b, v111
	v_exp_f32_e32 v101, v101
	v_cvt_pk_bf16_f32 v96, v96, v97
	v_add_f32_e32 v97, 1.0, v100
	v_rcp_f32_e32 v97, v97
	v_add_f32_e32 v100, 1.0, v101
	v_rcp_f32_e32 v100, v100
	v_pk_mul_f32 v[102:103], v[102:103], v[164:165] op_sel_hi:[1,0]
	v_pk_mul_f32 v[104:105], v[104:105], v[164:165] op_sel_hi:[1,0]
	v_mul_f32_e32 v101, v110, v102
	v_mul_f32_e32 v97, v101, v97
	v_mul_f32_e32 v101, v111, v103
	v_mul_f32_e32 v100, v101, v100
	v_mul_f32_e32 v101, 0xbfb8aa3b, v104
	v_exp_f32_e32 v101, v101
	v_mul_f32_e32 v102, 0xbfb8aa3b, v105
	v_exp_f32_e32 v102, v102
	v_cvt_pk_bf16_f32 v97, v97, v100
	v_add_f32_e32 v100, 1.0, v101
	v_rcp_f32_e32 v100, v100
	v_add_f32_e32 v101, 1.0, v102
	v_rcp_f32_e32 v101, v101
	v_pk_mul_f32 v[106:107], v[106:107], v[164:165] op_sel_hi:[1,0]
	v_mul_f32_e32 v98, v104, v98
	v_mul_f32_e32 v98, v98, v100
	v_mul_f32_e32 v99, v105, v99
	v_mul_f32_e32 v100, 0xbfb8aa3b, v106
	v_mul_f32_e32 v99, v99, v101
	v_exp_f32_e32 v100, v100
	v_mul_f32_e32 v101, 0xbfb8aa3b, v107
	v_exp_f32_e32 v101, v101
	v_cvt_pk_bf16_f32 v98, v98, v99
	v_add_f32_e32 v99, 1.0, v100
	v_rcp_f32_e32 v99, v99
	v_add_f32_e32 v100, 1.0, v101
	v_rcp_f32_e32 v100, v100
	v_mul_f32_e32 v101, v106, v116
	v_mul_f32_e32 v99, v101, v99
	v_mul_f32_e32 v101, v107, v117
	v_add_u32_e32 v118, s11, v151
	v_mul_f32_e32 v100, v101, v100
	v_cvt_pk_bf16_f32 v99, v99, v100
	v_mad_i64_i32 v[100:101], s[22:23], v118, s48, v[112:113]
	v_lshl_add_u64 v[100:101], v[100:101], 0, v[114:115]
	v_pk_mul_f32 v[92:93], v[92:93], v[166:167] op_sel_hi:[1,0]
	global_store_dwordx4 v[100:101], v[96:99], off
	v_pk_mul_f32 v[84:85], v[84:85], v[166:167] op_sel_hi:[1,0]
	v_pk_mul_f32 v[94:95], v[94:95], v[166:167] op_sel_hi:[1,0]
	v_pk_mul_f32 v[96:97], v[82:83], v[166:167] op_sel_hi:[1,0]
	v_mul_f32_e32 v82, 0xbfb8aa3b, v92
	v_exp_f32_e32 v99, v82
	v_mul_f32_e32 v82, 0xbfb8aa3b, v93
	v_exp_f32_e32 v100, v82
	v_pk_mul_f32 v[82:83], v[80:81], v[166:167] op_sel_hi:[1,0]
	v_add_f32_e32 v80, 1.0, v99
	v_rcp_f32_e32 v80, v80
	v_add_f32_e32 v81, 1.0, v100
	v_rcp_f32_e32 v81, v81
	v_mul_f32_e32 v84, v92, v84
	v_mul_f32_e32 v80, v84, v80
	v_mul_f32_e32 v84, v93, v85
	v_mul_f32_e32 v81, v84, v81
	v_mul_f32_e32 v84, 0xbfb8aa3b, v94
	v_exp_f32_e32 v84, v84
	v_mul_f32_e32 v85, 0xbfb8aa3b, v95
	v_exp_f32_e32 v85, v85
	v_cvt_pk_bf16_f32 v80, v80, v81
	v_add_f32_e32 v81, 1.0, v84
	v_rcp_f32_e32 v81, v81
	v_add_f32_e32 v84, 1.0, v85
	v_rcp_f32_e32 v84, v84
	v_pk_mul_f32 v[86:87], v[86:87], v[166:167] op_sel_hi:[1,0]
	v_pk_mul_f32 v[88:89], v[88:89], v[166:167] op_sel_hi:[1,0]
	v_mul_f32_e32 v85, v94, v86
	v_mul_f32_e32 v81, v85, v81
	v_mul_f32_e32 v85, v95, v87
	v_mul_f32_e32 v84, v85, v84
	v_mul_f32_e32 v85, 0xbfb8aa3b, v88
	v_exp_f32_e32 v85, v85
	v_mul_f32_e32 v86, 0xbfb8aa3b, v89
	v_exp_f32_e32 v86, v86
	v_cvt_pk_bf16_f32 v81, v81, v84
	v_add_f32_e32 v84, 1.0, v85
	v_rcp_f32_e32 v84, v84
	v_add_f32_e32 v85, 1.0, v86
	v_rcp_f32_e32 v85, v85
	v_pk_mul_f32 v[90:91], v[90:91], v[166:167] op_sel_hi:[1,0]
	v_mul_f32_e32 v82, v88, v82
	v_mul_f32_e32 v82, v82, v84
	v_mul_f32_e32 v83, v89, v83
	v_mul_f32_e32 v84, 0xbfb8aa3b, v90
	v_mul_f32_e32 v83, v83, v85
	v_exp_f32_e32 v84, v84
	v_mul_f32_e32 v85, 0xbfb8aa3b, v91
	v_exp_f32_e32 v85, v85
	v_cvt_pk_bf16_f32 v82, v82, v83
	v_add_f32_e32 v83, 1.0, v84
	v_rcp_f32_e32 v83, v83
	v_add_f32_e32 v84, 1.0, v85
	v_rcp_f32_e32 v84, v84
	v_rsq_f32_e32 v148, v163
	v_mul_f32_e32 v85, v90, v96
	v_mul_f32_e32 v83, v85, v83
	v_mul_f32_e32 v85, v91, v97
	v_add_u32_e32 v98, s11, v152
	v_mul_f32_e32 v84, v85, v84
	v_cvt_pk_bf16_f32 v83, v83, v84
	v_mad_i64_i32 v[84:85], s[22:23], v98, s48, v[112:113]
	v_lshl_add_u64 v[84:85], v[84:85], 0, v[114:115]
	v_pk_mul_f32 v[76:77], v[76:77], v[148:149] op_sel_hi:[1,0]
	global_store_dwordx4 v[84:85], v[80:83], off
	v_pk_mul_f32 v[68:69], v[68:69], v[148:149] op_sel_hi:[1,0]
	v_pk_mul_f32 v[78:79], v[78:79], v[148:149] op_sel_hi:[1,0]
	v_pk_mul_f32 v[80:81], v[66:67], v[148:149] op_sel_hi:[1,0]
	v_mul_f32_e32 v66, 0xbfb8aa3b, v76
	v_exp_f32_e32 v83, v66
	v_mul_f32_e32 v66, 0xbfb8aa3b, v77
	v_exp_f32_e32 v84, v66
	v_pk_mul_f32 v[66:67], v[64:65], v[148:149] op_sel_hi:[1,0]
	v_add_f32_e32 v64, 1.0, v83
	v_rcp_f32_e32 v64, v64
	v_add_f32_e32 v65, 1.0, v84
	v_rcp_f32_e32 v65, v65
	v_mul_f32_e32 v68, v76, v68
	v_mul_f32_e32 v64, v68, v64
	v_mul_f32_e32 v68, v77, v69
	v_mul_f32_e32 v65, v68, v65
	v_mul_f32_e32 v68, 0xbfb8aa3b, v78
	v_exp_f32_e32 v68, v68
	v_mul_f32_e32 v69, 0xbfb8aa3b, v79
	v_exp_f32_e32 v69, v69
	v_cvt_pk_bf16_f32 v64, v64, v65
	v_add_f32_e32 v65, 1.0, v68
	v_rcp_f32_e32 v65, v65
	v_add_f32_e32 v68, 1.0, v69
	v_rcp_f32_e32 v68, v68
	v_pk_mul_f32 v[70:71], v[70:71], v[148:149] op_sel_hi:[1,0]
	v_pk_mul_f32 v[72:73], v[72:73], v[148:149] op_sel_hi:[1,0]
	v_mul_f32_e32 v69, v78, v70
	v_mul_f32_e32 v65, v69, v65
	v_mul_f32_e32 v69, v79, v71
	v_mul_f32_e32 v68, v69, v68
	v_mul_f32_e32 v69, 0xbfb8aa3b, v72
	v_exp_f32_e32 v69, v69
	v_mul_f32_e32 v70, 0xbfb8aa3b, v73
	v_exp_f32_e32 v70, v70
	v_cvt_pk_bf16_f32 v65, v65, v68
	v_add_f32_e32 v68, 1.0, v69
	v_rcp_f32_e32 v68, v68
	v_add_f32_e32 v69, 1.0, v70
	v_rcp_f32_e32 v69, v69
	v_pk_mul_f32 v[74:75], v[74:75], v[148:149] op_sel_hi:[1,0]
	v_mul_f32_e32 v66, v72, v66
	v_mul_f32_e32 v66, v66, v68
	v_mul_f32_e32 v67, v73, v67
	v_mul_f32_e32 v68, 0xbfb8aa3b, v74
	v_mul_f32_e32 v67, v67, v69
	v_exp_f32_e32 v68, v68
	v_mul_f32_e32 v69, 0xbfb8aa3b, v75
	v_exp_f32_e32 v69, v69
	v_cvt_pk_bf16_f32 v66, v66, v67
	v_add_f32_e32 v67, 1.0, v68
	v_rcp_f32_e32 v67, v67
	v_add_f32_e32 v68, 1.0, v69
	v_rcp_f32_e32 v68, v68
	v_mul_f32_e32 v69, v74, v80
	v_mul_f32_e32 v67, v69, v67
	v_mul_f32_e32 v69, v75, v81
	v_add_u32_e32 v82, s11, v153
	v_mul_f32_e32 v68, v69, v68
	v_cvt_pk_bf16_f32 v67, v67, v68
	v_mad_i64_i32 v[68:69], s[22:23], v82, s48, v[112:113]
	v_add_u32_e32 v88, 0x80, v146
	v_lshl_add_u64 v[68:69], v[68:69], 0, v[114:115]
	v_ashrrev_i32_e32 v89, 31, v88
	global_store_dwordx4 v[68:69], v[64:67], off
	v_add_u32_e32 v70, 0x90, v146
	v_ashrrev_i32_e32 v71, 31, v70
	v_lshlrev_b64 v[64:65], 6, v[88:89]
	v_lshl_add_u64 v[64:65], v[136:137], 0, v[64:65]
	s_waitcnt vmcnt(4)
	v_mov_b32_e32 v72, v236
	v_mov_b32_e32 v73, v237
	v_mov_b32_e32 v74, v238
	v_mov_b32_e32 v75, v239
	v_lshlrev_b64 v[64:65], 6, v[70:71]
	v_lshl_add_u64 v[64:65], v[136:137], 0, v[64:65]
	v_mov_b32_e32 v76, v240
	v_mov_b32_e32 v77, v241
	v_mov_b32_e32 v78, v242
	v_mov_b32_e32 v79, v243
	v_add_u32_e32 v66, 0xa0, v146
	v_ashrrev_i32_e32 v67, 31, v66
	v_lshlrev_b64 v[64:65], 6, v[66:67]
	v_lshl_add_u64 v[64:65], v[136:137], 0, v[64:65]
	v_mov_b32_e32 v80, v244
	v_mov_b32_e32 v81, v245
	v_mov_b32_e32 v82, v246
	v_mov_b32_e32 v83, v247
	v_add_u32_e32 v64, 0xb0, v146
	v_ashrrev_i32_e32 v65, 31, v64
	v_lshlrev_b64 v[68:69], 6, v[64:65]
	v_lshl_add_u64 v[68:69], v[136:137], 0, v[68:69]
	v_mov_b32_e32 v84, v248
	v_mov_b32_e32 v85, v249
	v_mov_b32_e32 v86, v250
	v_mov_b32_e32 v87, v251
	s_andn2_b64 vcc, exec, s[0:1]
	s_mov_b64 s[0:1], -1
	v_mov_b32_e32 v68, v73
	v_mov_b32_e32 v69, v74
	v_mov_b32_e32 v73, v75
	v_pk_add_f32 v[68:69], v[68:69], v[72:73]
	s_nop 0
	v_add_f32_e32 v65, v68, v69
	ds_bpermute_b32 v67, v160, v65
	v_mov_b32_e32 v68, v77
	v_mov_b32_e32 v69, v78
	v_mov_b32_e32 v77, v79
	v_pk_add_f32 v[68:69], v[68:69], v[76:77]
	s_waitcnt lgkmcnt(0)
	v_add_f32_e32 v65, v65, v67
	ds_bpermute_b32 v67, v147, v65
	v_add_f32_e32 v68, v68, v69
	ds_bpermute_b32 v69, v160, v68
	s_waitcnt lgkmcnt(1)
	v_add_f32_e32 v65, v65, v67
	v_fmamk_f32 v65, v65, 0x3a800000, v159
	v_rsq_f32_e32 v72, v65
	s_waitcnt lgkmcnt(0)
	v_add_f32_e32 v65, v68, v69
	v_mov_b32_e32 v68, v81
	v_mov_b32_e32 v69, v82
	v_mov_b32_e32 v81, v83
	v_pk_add_f32 v[68:69], v[68:69], v[80:81]
	ds_bpermute_b32 v67, v147, v65
	v_add_f32_e32 v71, v68, v69
	v_mov_b32_e32 v68, v85
	v_mov_b32_e32 v69, v86
	v_mov_b32_e32 v85, v87
	ds_bpermute_b32 v73, v160, v71
	v_pk_add_f32 v[68:69], v[68:69], v[84:85]
	s_waitcnt lgkmcnt(1)
	v_add_f32_e32 v65, v65, v67
	v_add_f32_e32 v68, v68, v69
	ds_bpermute_b32 v69, v160, v68
	s_waitcnt lgkmcnt(1)
	v_add_f32_e32 v67, v71, v73
	ds_bpermute_b32 v71, v147, v67
	v_fmamk_f32 v65, v65, 0x3a800000, v159
	v_rsq_f32_e32 v74, v65
	s_waitcnt lgkmcnt(1)
	v_add_f32_e32 v68, v68, v69
	ds_bpermute_b32 v69, v147, v68
	s_waitcnt lgkmcnt(1)
	v_add_f32_e32 v65, v67, v71
	v_fmamk_f32 v65, v65, 0x3a800000, v159
	v_rsq_f32_e32 v76, v65
	v_pk_mul_f32 v[60:61], v[60:61], v[72:73] op_sel_hi:[1,0]
	s_waitcnt lgkmcnt(0)
	v_add_f32_e32 v65, v68, v69
	v_fmamk_f32 v65, v65, 0x3a800000, v159
	v_pk_mul_f32 v[78:79], v[50:51], v[72:73] op_sel_hi:[1,0]
	v_mul_f32_e32 v50, 0xbfb8aa3b, v60
	v_rsq_f32_e32 v68, v65
	v_exp_f32_e32 v65, v50
	v_mul_f32_e32 v50, 0xbfb8aa3b, v61
	v_exp_f32_e32 v67, v50
	v_pk_mul_f32 v[50:51], v[48:49], v[72:73] op_sel_hi:[1,0]
	v_add_f32_e32 v48, 1.0, v65
	v_rcp_f32_e32 v48, v48
	v_add_f32_e32 v49, 1.0, v67
	v_rcp_f32_e32 v49, v49
	v_pk_mul_f32 v[52:53], v[52:53], v[72:73] op_sel_hi:[1,0]
	v_pk_mul_f32 v[62:63], v[62:63], v[72:73] op_sel_hi:[1,0]
	v_mul_f32_e32 v52, v60, v52
	v_mul_f32_e32 v48, v52, v48
	v_mul_f32_e32 v52, v61, v53
	v_mul_f32_e32 v49, v52, v49
	v_mul_f32_e32 v52, 0xbfb8aa3b, v62
	v_exp_f32_e32 v52, v52
	v_mul_f32_e32 v53, 0xbfb8aa3b, v63
	v_exp_f32_e32 v53, v53
	v_cvt_pk_bf16_f32 v48, v48, v49
	v_add_f32_e32 v49, 1.0, v52
	v_rcp_f32_e32 v49, v49
	v_add_f32_e32 v52, 1.0, v53
	v_rcp_f32_e32 v52, v52
	v_pk_mul_f32 v[54:55], v[54:55], v[72:73] op_sel_hi:[1,0]
	v_pk_mul_f32 v[56:57], v[56:57], v[72:73] op_sel_hi:[1,0]
	v_mul_f32_e32 v53, v62, v54
	v_mul_f32_e32 v49, v53, v49
	v_mul_f32_e32 v53, v63, v55
	v_mul_f32_e32 v52, v53, v52
	v_mul_f32_e32 v53, 0xbfb8aa3b, v56
	v_exp_f32_e32 v53, v53
	v_mul_f32_e32 v54, 0xbfb8aa3b, v57
	v_exp_f32_e32 v54, v54
	v_cvt_pk_bf16_f32 v49, v49, v52
	v_add_f32_e32 v52, 1.0, v53
	v_rcp_f32_e32 v52, v52
	v_add_f32_e32 v53, 1.0, v54
	v_rcp_f32_e32 v53, v53
	v_pk_mul_f32 v[58:59], v[58:59], v[72:73] op_sel_hi:[1,0]
	v_mul_f32_e32 v50, v56, v50
	v_mul_f32_e32 v50, v50, v52
	v_mul_f32_e32 v51, v57, v51
	v_mul_f32_e32 v52, 0xbfb8aa3b, v58
	v_mul_f32_e32 v51, v51, v53
	v_exp_f32_e32 v52, v52
	v_mul_f32_e32 v53, 0xbfb8aa3b, v59
	v_exp_f32_e32 v53, v53
	v_cvt_pk_bf16_f32 v50, v50, v51
	v_add_f32_e32 v51, 1.0, v52
	v_rcp_f32_e32 v51, v51
	v_add_f32_e32 v52, 1.0, v53
	v_rcp_f32_e32 v52, v52
	v_mul_f32_e32 v53, v58, v78
	v_mul_f32_e32 v51, v53, v51
	v_mul_f32_e32 v53, v59, v79
	v_mul_f32_e32 v52, v53, v52
	v_cvt_pk_bf16_f32 v51, v51, v52
	v_mad_i64_i32 v[52:53], s[22:23], v88, s48, v[112:113]
	v_lshl_add_u64 v[52:53], v[52:53], 0, v[114:115]
	v_pk_mul_f32 v[44:45], v[44:45], v[74:75] op_sel_hi:[1,0]
	global_store_dwordx4 v[52:53], v[48:51], off
	v_pk_mul_f32 v[36:37], v[36:37], v[74:75] op_sel_hi:[1,0]
	v_pk_mul_f32 v[46:47], v[46:47], v[74:75] op_sel_hi:[1,0]
	v_pk_mul_f32 v[48:49], v[34:35], v[74:75] op_sel_hi:[1,0]
	v_mul_f32_e32 v34, 0xbfb8aa3b, v44
	v_exp_f32_e32 v50, v34
	v_mul_f32_e32 v34, 0xbfb8aa3b, v45
	v_exp_f32_e32 v51, v34
	v_pk_mul_f32 v[34:35], v[32:33], v[74:75] op_sel_hi:[1,0]
	v_add_f32_e32 v32, 1.0, v50
	v_rcp_f32_e32 v32, v32
	v_add_f32_e32 v33, 1.0, v51
	v_rcp_f32_e32 v33, v33
	v_mul_f32_e32 v36, v44, v36
	v_mul_f32_e32 v32, v36, v32
	v_mul_f32_e32 v36, v45, v37
	v_mul_f32_e32 v33, v36, v33
	v_mul_f32_e32 v36, 0xbfb8aa3b, v46
	v_exp_f32_e32 v36, v36
	v_mul_f32_e32 v37, 0xbfb8aa3b, v47
	v_exp_f32_e32 v37, v37
	v_cvt_pk_bf16_f32 v32, v32, v33
	v_add_f32_e32 v33, 1.0, v36
	v_rcp_f32_e32 v33, v33
	v_add_f32_e32 v36, 1.0, v37
	v_rcp_f32_e32 v36, v36
	v_pk_mul_f32 v[38:39], v[38:39], v[74:75] op_sel_hi:[1,0]
	v_pk_mul_f32 v[40:41], v[40:41], v[74:75] op_sel_hi:[1,0]
	v_mul_f32_e32 v37, v46, v38
	v_mul_f32_e32 v33, v37, v33
	v_mul_f32_e32 v37, v47, v39
	v_mul_f32_e32 v36, v37, v36
	v_mul_f32_e32 v37, 0xbfb8aa3b, v40
	v_exp_f32_e32 v37, v37
	v_mul_f32_e32 v38, 0xbfb8aa3b, v41
	v_exp_f32_e32 v38, v38
	v_cvt_pk_bf16_f32 v33, v33, v36
	v_add_f32_e32 v36, 1.0, v37
	v_rcp_f32_e32 v36, v36
	v_add_f32_e32 v37, 1.0, v38
	v_rcp_f32_e32 v37, v37
	v_pk_mul_f32 v[42:43], v[42:43], v[74:75] op_sel_hi:[1,0]
	v_mul_f32_e32 v34, v40, v34
	v_mul_f32_e32 v34, v34, v36
	v_mul_f32_e32 v35, v41, v35
	v_mul_f32_e32 v36, 0xbfb8aa3b, v42
	v_mul_f32_e32 v35, v35, v37
	v_exp_f32_e32 v36, v36
	v_mul_f32_e32 v37, 0xbfb8aa3b, v43
	v_exp_f32_e32 v37, v37
	v_cvt_pk_bf16_f32 v34, v34, v35
	v_add_f32_e32 v35, 1.0, v36
	v_rcp_f32_e32 v35, v35
	v_add_f32_e32 v36, 1.0, v37
	v_rcp_f32_e32 v36, v36
	v_mul_f32_e32 v37, v42, v48
	v_mul_f32_e32 v35, v37, v35
	v_mul_f32_e32 v37, v43, v49
	v_mul_f32_e32 v36, v37, v36
	v_cvt_pk_bf16_f32 v35, v35, v36
	v_mad_i64_i32 v[36:37], s[22:23], v70, s48, v[112:113]
	v_lshl_add_u64 v[36:37], v[36:37], 0, v[114:115]
	v_pk_mul_f32 v[28:29], v[28:29], v[76:77] op_sel_hi:[1,0]
	global_store_dwordx4 v[36:37], v[32:35], off
	v_pk_mul_f32 v[20:21], v[20:21], v[76:77] op_sel_hi:[1,0]
	v_pk_mul_f32 v[30:31], v[30:31], v[76:77] op_sel_hi:[1,0]
	v_pk_mul_f32 v[32:33], v[18:19], v[76:77] op_sel_hi:[1,0]
	v_mul_f32_e32 v18, 0xbfb8aa3b, v28
	v_exp_f32_e32 v34, v18
	v_mul_f32_e32 v18, 0xbfb8aa3b, v29
	v_exp_f32_e32 v35, v18
	v_pk_mul_f32 v[18:19], v[16:17], v[76:77] op_sel_hi:[1,0]
	v_add_f32_e32 v16, 1.0, v34
	v_rcp_f32_e32 v16, v16
	v_add_f32_e32 v17, 1.0, v35
	v_rcp_f32_e32 v17, v17
	v_mul_f32_e32 v20, v28, v20
	v_mul_f32_e32 v16, v20, v16
	v_mul_f32_e32 v20, v29, v21
	v_mul_f32_e32 v17, v20, v17
	v_mul_f32_e32 v20, 0xbfb8aa3b, v30
	v_exp_f32_e32 v20, v20
	v_mul_f32_e32 v21, 0xbfb8aa3b, v31
	v_exp_f32_e32 v21, v21
	v_cvt_pk_bf16_f32 v16, v16, v17
	v_add_f32_e32 v17, 1.0, v20
	v_rcp_f32_e32 v17, v17
	v_add_f32_e32 v20, 1.0, v21
	v_rcp_f32_e32 v20, v20
	v_pk_mul_f32 v[22:23], v[22:23], v[76:77] op_sel_hi:[1,0]
	v_pk_mul_f32 v[24:25], v[24:25], v[76:77] op_sel_hi:[1,0]
	v_mul_f32_e32 v21, v30, v22
	v_mul_f32_e32 v17, v21, v17
	v_mul_f32_e32 v21, v31, v23
	v_mul_f32_e32 v20, v21, v20
	v_mul_f32_e32 v21, 0xbfb8aa3b, v24
	v_exp_f32_e32 v21, v21
	v_mul_f32_e32 v22, 0xbfb8aa3b, v25
	v_exp_f32_e32 v22, v22
	v_cvt_pk_bf16_f32 v17, v17, v20
	v_add_f32_e32 v20, 1.0, v21
	v_rcp_f32_e32 v20, v20
	v_add_f32_e32 v21, 1.0, v22
	v_rcp_f32_e32 v21, v21
	v_pk_mul_f32 v[26:27], v[26:27], v[76:77] op_sel_hi:[1,0]
	v_mul_f32_e32 v18, v24, v18
	v_mul_f32_e32 v18, v18, v20
	v_mul_f32_e32 v19, v25, v19
	v_mul_f32_e32 v20, 0xbfb8aa3b, v26
	v_mul_f32_e32 v19, v19, v21
	v_exp_f32_e32 v20, v20
	v_mul_f32_e32 v21, 0xbfb8aa3b, v27
	v_exp_f32_e32 v21, v21
	v_cvt_pk_bf16_f32 v18, v18, v19
	v_add_f32_e32 v19, 1.0, v20
	v_rcp_f32_e32 v19, v19
	v_add_f32_e32 v20, 1.0, v21
	v_rcp_f32_e32 v20, v20
	v_mul_f32_e32 v21, v26, v32
	v_mul_f32_e32 v19, v21, v19
	v_mul_f32_e32 v21, v27, v33
	v_mul_f32_e32 v20, v21, v20
	v_cvt_pk_bf16_f32 v19, v19, v20
	v_mad_i64_i32 v[20:21], s[22:23], v66, s48, v[112:113]
	v_lshl_add_u64 v[20:21], v[20:21], 0, v[114:115]
	v_pk_mul_f32 v[12:13], v[12:13], v[68:69] op_sel_hi:[1,0]
	global_store_dwordx4 v[20:21], v[16:19], off
	v_pk_mul_f32 v[4:5], v[4:5], v[68:69] op_sel_hi:[1,0]
	v_pk_mul_f32 v[14:15], v[14:15], v[68:69] op_sel_hi:[1,0]
	v_pk_mul_f32 v[16:17], v[2:3], v[68:69] op_sel_hi:[1,0]
	v_mul_f32_e32 v2, 0xbfb8aa3b, v12
	v_exp_f32_e32 v18, v2
	v_mul_f32_e32 v2, 0xbfb8aa3b, v13
	v_exp_f32_e32 v19, v2
	v_pk_mul_f32 v[2:3], v[0:1], v[68:69] op_sel_hi:[1,0]
	v_add_f32_e32 v0, 1.0, v18
	v_rcp_f32_e32 v0, v0
	v_add_f32_e32 v1, 1.0, v19
	v_rcp_f32_e32 v1, v1
	v_mul_f32_e32 v4, v12, v4
	v_mul_f32_e32 v0, v4, v0
	v_mul_f32_e32 v4, v13, v5
	v_mul_f32_e32 v1, v4, v1
	v_mul_f32_e32 v4, 0xbfb8aa3b, v14
	v_exp_f32_e32 v4, v4
	v_mul_f32_e32 v5, 0xbfb8aa3b, v15
	v_exp_f32_e32 v5, v5
	v_cvt_pk_bf16_f32 v0, v0, v1
	v_add_f32_e32 v1, 1.0, v4
	v_rcp_f32_e32 v1, v1
	v_add_f32_e32 v4, 1.0, v5
	v_rcp_f32_e32 v4, v4
	v_pk_mul_f32 v[6:7], v[6:7], v[68:69] op_sel_hi:[1,0]
	v_pk_mul_f32 v[8:9], v[8:9], v[68:69] op_sel_hi:[1,0]
	v_mul_f32_e32 v5, v14, v6
	v_mul_f32_e32 v1, v5, v1
	v_mul_f32_e32 v5, v15, v7
	v_mul_f32_e32 v4, v5, v4
	v_mul_f32_e32 v5, 0xbfb8aa3b, v8
	v_exp_f32_e32 v5, v5
	v_mul_f32_e32 v6, 0xbfb8aa3b, v9
	v_exp_f32_e32 v6, v6
	v_cvt_pk_bf16_f32 v1, v1, v4
	v_add_f32_e32 v4, 1.0, v5
	v_rcp_f32_e32 v4, v4
	v_add_f32_e32 v5, 1.0, v6
	v_rcp_f32_e32 v5, v5
	v_pk_mul_f32 v[10:11], v[10:11], v[68:69] op_sel_hi:[1,0]
	v_mul_f32_e32 v2, v8, v2
	v_mul_f32_e32 v2, v2, v4
	v_mul_f32_e32 v3, v9, v3
	v_mul_f32_e32 v4, 0xbfb8aa3b, v10
	v_mul_f32_e32 v3, v3, v5
	v_exp_f32_e32 v4, v4
	v_mul_f32_e32 v5, 0xbfb8aa3b, v11
	v_exp_f32_e32 v5, v5
	v_cvt_pk_bf16_f32 v2, v2, v3
	v_add_f32_e32 v3, 1.0, v4
	v_rcp_f32_e32 v3, v3
	v_add_f32_e32 v4, 1.0, v5
	v_rcp_f32_e32 v4, v4
	v_mul_f32_e32 v5, v10, v16
	v_mul_f32_e32 v3, v5, v3
	v_mul_f32_e32 v5, v11, v17
	v_mul_f32_e32 v4, v5, v4
	v_cvt_pk_bf16_f32 v3, v3, v4
	v_mad_i64_i32 v[4:5], s[22:23], v64, s48, v[112:113]
	v_lshl_add_u64 v[4:5], v[4:5], 0, v[114:115]
	global_store_dwordx4 v[4:5], v[0:3], off
	s_cbranch_vccnz .LBB0_157
	s_andn2_b64 vcc, exec, s[4:5]
	s_cbranch_vccnz .LBB0_156
	s_barrier
	s_branch .LBB0_156

.LBB0_882:
	s_lshl_b32 s11, s18, 8
	v_add_u32_e32 v146, s11, v149
	v_or_b32_e32 v162, 16, v146
	v_ashrrev_i32_e32 v147, 31, v146
	v_ashrrev_i32_e32 v163, 31, v162
	v_lshlrev_b64 v[160:161], 6, v[146:147]
	v_lshlrev_b64 v[162:163], 6, v[162:163]
	v_lshl_add_u64 v[160:161], v[136:137], 0, v[160:161]
	v_lshl_add_u64 v[166:167], v[136:137], 0, v[162:163]
	v_mov_b32_e32 v162, v236
	v_mov_b32_e32 v163, v237
	v_mov_b32_e32 v164, v238
	v_mov_b32_e32 v165, v239
	v_mov_b32_e32 v166, v240
	v_mov_b32_e32 v167, v241
	v_mov_b32_e32 v168, v242
	v_mov_b32_e32 v169, v243
	v_or_b32_e32 v160, 32, v146
	v_ashrrev_i32_e32 v161, 31, v160
	v_lshlrev_b64 v[160:161], 6, v[160:161]
	v_lshl_add_u64 v[160:161], v[136:137], 0, v[160:161]
	v_mov_b32_e32 v170, v244
	v_mov_b32_e32 v171, v245
	v_mov_b32_e32 v172, v246
	v_mov_b32_e32 v173, v247
	v_or_b32_e32 v160, 48, v146
	v_ashrrev_i32_e32 v161, 31, v160
	v_lshlrev_b64 v[160:161], 6, v[160:161]
	v_lshl_add_u64 v[160:161], v[136:137], 0, v[160:161]
	v_mov_b32_e32 v174, v248
	v_mov_b32_e32 v175, v249
	v_mov_b32_e32 v176, v250
	v_mov_b32_e32 v177, v251
	v_add_u32_e32 v252, 0x80, v146
	v_mov_b32_e32 v253, 0
	v_lshlrev_b64 v[252:253], 6, v[252:253]
	v_lshl_add_u64 v[252:253], v[136:137], 0, v[252:253]
	global_load_dwordx4 v[236:239], v[252:253], off
	global_load_dwordx4 v[240:243], v[252:253], off offset:1024
	global_load_dwordx4 v[244:247], v[252:253], off offset:2048
	global_load_dwordx4 v[248:251], v[252:253], off offset:3072
	v_and_b32_e32 v148, 64, v158
	v_xor_b32_e32 v147, 16, v158
	v_add_u32_e32 v148, 64, v148
	v_xor_b32_e32 v160, 32, v158
	v_cmp_lt_i32_e32 vcc, v147, v148
	v_lshl_or_b32 v178, s69, 7, v154
	v_ashrrev_i32_e32 v179, 31, v178
	v_cndmask_b32_e32 v147, v158, v147, vcc
	v_cmp_lt_i32_e32 vcc, v160, v148
	v_mov_b32_e32 v180, v163
	v_mov_b32_e32 v181, v164
	v_mov_b32_e32 v163, v165
	v_cndmask_b32_e32 v148, v158, v160, vcc
	v_pk_add_f32 v[162:163], v[180:181], v[162:163]
	v_lshlrev_b32_e32 v160, 2, v147
	v_lshlrev_b32_e32 v147, 2, v148
	v_mov_b32_e32 v164, v167
	v_mov_b32_e32 v165, v168
	v_mov_b32_e32 v167, v169
	v_add_f32_e32 v148, v162, v163
	v_mov_b32_e32 v168, v171
	v_mov_b32_e32 v169, v172
	v_mov_b32_e32 v171, v173
	v_pk_add_f32 v[162:163], v[164:165], v[166:167]
	ds_bpermute_b32 v161, v160, v148
	v_mov_b32_e32 v172, v175
	v_mov_b32_e32 v173, v176
	v_mov_b32_e32 v175, v177
	v_pk_add_f32 v[164:165], v[168:169], v[170:171]
	v_add_f32_e32 v162, v162, v163
	v_pk_add_f32 v[166:167], v[172:173], v[174:175]
	v_add_f32_e32 v163, v164, v165
	ds_bpermute_b32 v165, v160, v162
	v_add_f32_e32 v164, v166, v167
	ds_bpermute_b32 v166, v160, v163
	ds_bpermute_b32 v167, v160, v164
	s_waitcnt lgkmcnt(3)
	v_add_f32_e32 v148, v148, v161
	ds_bpermute_b32 v161, v147, v148
	s_waitcnt lgkmcnt(3)
	v_add_f32_e32 v162, v162, v165
	ds_bpermute_b32 v165, v147, v162
	s_waitcnt lgkmcnt(3)
	v_add_f32_e32 v163, v163, v166
	s_waitcnt lgkmcnt(2)
	v_add_f32_e32 v164, v164, v167
	ds_bpermute_b32 v166, v147, v163
	ds_bpermute_b32 v167, v147, v164
	s_waitcnt lgkmcnt(3)
	v_add_f32_e32 v148, v148, v161
	v_fmamk_f32 v148, v148, 0x3a800000, v159
	s_waitcnt lgkmcnt(2)
	v_add_f32_e32 v161, v162, v165
	v_rsq_f32_e32 v162, v148
	s_waitcnt lgkmcnt(1)
	v_add_f32_e32 v163, v163, v166
	s_waitcnt lgkmcnt(0)
	v_add_f32_e32 v164, v164, v167
	v_fmamk_f32 v148, v161, 0x3a800000, v159
	v_fmamk_f32 v161, v163, 0x3a800000, v159
	v_fmamk_f32 v163, v164, 0x3a800000, v159
	v_pk_mul_f32 v[126:127], v[126:127], v[162:163] op_sel_hi:[1,0]
	v_pk_mul_f32 v[124:125], v[124:125], v[162:163] op_sel_hi:[1,0]
	v_pk_mul_f32 v[118:119], v[118:119], v[162:163] op_sel_hi:[1,0]
	v_pk_mul_f32 v[116:117], v[116:117], v[162:163] op_sel_hi:[1,0]
	v_mul_f32_e32 v118, v126, v118
	v_mul_f32_e32 v116, v124, v116
	v_mul_f32_e32 v124, 0xbfb8aa3b, v124
	v_mul_f32_e32 v117, v125, v117
	v_mul_f32_e32 v125, 0xbfb8aa3b, v125
	v_mul_f32_e32 v126, 0xbfb8aa3b, v126
	v_mul_f32_e32 v119, v127, v119
	v_mul_f32_e32 v127, 0xbfb8aa3b, v127
	v_exp_f32_e32 v124, v124
	v_exp_f32_e32 v125, v125
	v_exp_f32_e32 v126, v126
	v_exp_f32_e32 v127, v127
	v_pk_mul_f32 v[120:121], v[120:121], v[162:163] op_sel_hi:[1,0]
	v_pk_mul_f32 v[122:123], v[122:123], v[162:163] op_sel_hi:[1,0]
	v_pk_mul_f32 v[114:115], v[114:115], v[162:163] op_sel_hi:[1,0]
	v_pk_mul_f32 v[112:113], v[112:113], v[162:163] op_sel_hi:[1,0]
	v_mul_f32_e32 v162, 0xbfb8aa3b, v121
	v_add_f32_e32 v124, 1.0, v124
	v_add_f32_e32 v125, 1.0, v125
	v_add_f32_e32 v126, 1.0, v126
	v_exp_f32_e32 v162, v162
	v_add_f32_e32 v127, 1.0, v127
	v_rcp_f32_e32 v124, v124
	v_rcp_f32_e32 v125, v125
	v_rcp_f32_e32 v126, v126
	v_rcp_f32_e32 v127, v127
	v_rsq_f32_e32 v166, v161
	v_mul_f32_e32 v161, 0xbfb8aa3b, v120
	v_exp_f32_e32 v161, v161
	v_add_f32_e32 v162, 1.0, v162
	v_mul_f32_e32 v116, v116, v124
	v_mul_f32_e32 v117, v117, v125
	v_mul_f32_e32 v118, v118, v126
	v_mul_f32_e32 v119, v119, v127
	v_cvt_pk_bf16_f32 v116, v116, v117
	v_cvt_pk_bf16_f32 v117, v118, v119
	v_rcp_f32_e32 v118, v162
	v_add_f32_e32 v161, 1.0, v161
	v_mul_f32_e32 v113, v121, v113
	v_rcp_f32_e32 v161, v161
	v_mul_f32_e32 v113, v113, v118
	v_mul_f32_e32 v118, 0xbfb8aa3b, v122
	v_exp_f32_e32 v119, v118
	v_mul_f32_e32 v118, 0xbfb8aa3b, v123
	v_mul_f32_e32 v112, v120, v112
	v_exp_f32_e32 v120, v118
	v_mul_f32_e32 v112, v112, v161
	v_cvt_pk_bf16_f32 v118, v112, v113
	v_add_f32_e32 v112, 1.0, v119
	v_rcp_f32_e32 v112, v112
	v_add_f32_e32 v113, 1.0, v120
	v_rcp_f32_e32 v113, v113
	v_mul_f32_e32 v114, v122, v114
	v_rsq_f32_e32 v164, v148
	v_mul_f32_e32 v112, v114, v112
	v_mul_f32_e32 v114, v123, v115
	v_mul_f32_e32 v113, v114, v113
	v_cvt_pk_bf16_f32 v119, v112, v113
	v_mov_b64_e32 v[112:113], s[36:37]
	v_mad_i64_i32 v[120:121], s[22:23], v146, s68, v[112:113]
	v_lshlrev_b64 v[114:115], 1, v[178:179]
	v_lshl_add_u64 v[120:121], v[120:121], 0, v[114:115]
	v_pk_mul_f32 v[108:109], v[108:109], v[164:165] op_sel_hi:[1,0]
	global_store_dwordx4 v[120:121], v[116:119], off
	v_pk_mul_f32 v[100:101], v[100:101], v[164:165] op_sel_hi:[1,0]
	v_pk_mul_f32 v[110:111], v[110:111], v[164:165] op_sel_hi:[1,0]
	v_pk_mul_f32 v[116:117], v[98:99], v[164:165] op_sel_hi:[1,0]
	v_mul_f32_e32 v98, 0xbfb8aa3b, v108
	v_exp_f32_e32 v119, v98
	v_mul_f32_e32 v98, 0xbfb8aa3b, v109
	v_exp_f32_e32 v120, v98
	v_pk_mul_f32 v[98:99], v[96:97], v[164:165] op_sel_hi:[1,0]
	v_add_f32_e32 v96, 1.0, v119
	v_rcp_f32_e32 v96, v96
	v_add_f32_e32 v97, 1.0, v120
	v_rcp_f32_e32 v97, v97
	v_mul_f32_e32 v100, v108, v100
	v_mul_f32_e32 v96, v100, v96
	v_mul_f32_e32 v100, v109, v101
	v_mul_f32_e32 v97, v100, v97
	v_mul_f32_e32 v100, 0xbfb8aa3b, v110
	v_exp_f32_e32 v100, v100
	v_mul_f32_e32 v101, 0xbfb8aa3b, v111
	v_exp_f32_e32 v101, v101
	v_cvt_pk_bf16_f32 v96, v96, v97
	v_add_f32_e32 v97, 1.0, v100
	v_rcp_f32_e32 v97, v97
	v_add_f32_e32 v100, 1.0, v101
	v_rcp_f32_e32 v100, v100
	v_pk_mul_f32 v[102:103], v[102:103], v[164:165] op_sel_hi:[1,0]
	v_pk_mul_f32 v[104:105], v[104:105], v[164:165] op_sel_hi:[1,0]
	v_mul_f32_e32 v101, v110, v102
	v_mul_f32_e32 v97, v101, v97
	v_mul_f32_e32 v101, v111, v103
	v_mul_f32_e32 v100, v101, v100
	v_mul_f32_e32 v101, 0xbfb8aa3b, v104
	v_exp_f32_e32 v101, v101
	v_mul_f32_e32 v102, 0xbfb8aa3b, v105
	v_exp_f32_e32 v102, v102
	v_cvt_pk_bf16_f32 v97, v97, v100
	v_add_f32_e32 v100, 1.0, v101
	v_rcp_f32_e32 v100, v100
	v_add_f32_e32 v101, 1.0, v102
	v_rcp_f32_e32 v101, v101
	v_pk_mul_f32 v[106:107], v[106:107], v[164:165] op_sel_hi:[1,0]
	v_mul_f32_e32 v98, v104, v98
	v_mul_f32_e32 v98, v98, v100
	v_mul_f32_e32 v99, v105, v99
	v_mul_f32_e32 v100, 0xbfb8aa3b, v106
	v_mul_f32_e32 v99, v99, v101
	v_exp_f32_e32 v100, v100
	v_mul_f32_e32 v101, 0xbfb8aa3b, v107
	v_exp_f32_e32 v101, v101
	v_cvt_pk_bf16_f32 v98, v98, v99
	v_add_f32_e32 v99, 1.0, v100
	v_rcp_f32_e32 v99, v99
	v_add_f32_e32 v100, 1.0, v101
	v_rcp_f32_e32 v100, v100
	v_mul_f32_e32 v101, v106, v116
	v_mul_f32_e32 v99, v101, v99
	v_mul_f32_e32 v101, v107, v117
	v_add_u32_e32 v118, s11, v151
	v_mul_f32_e32 v100, v101, v100
	v_cvt_pk_bf16_f32 v99, v99, v100
	v_mad_i64_i32 v[100:101], s[22:23], v118, s68, v[112:113]
	v_lshl_add_u64 v[100:101], v[100:101], 0, v[114:115]
	v_pk_mul_f32 v[92:93], v[92:93], v[166:167] op_sel_hi:[1,0]
	global_store_dwordx4 v[100:101], v[96:99], off
	v_pk_mul_f32 v[84:85], v[84:85], v[166:167] op_sel_hi:[1,0]
	v_pk_mul_f32 v[94:95], v[94:95], v[166:167] op_sel_hi:[1,0]
	v_pk_mul_f32 v[96:97], v[82:83], v[166:167] op_sel_hi:[1,0]
	v_mul_f32_e32 v82, 0xbfb8aa3b, v92
	v_exp_f32_e32 v99, v82
	v_mul_f32_e32 v82, 0xbfb8aa3b, v93
	v_exp_f32_e32 v100, v82
	v_pk_mul_f32 v[82:83], v[80:81], v[166:167] op_sel_hi:[1,0]
	v_add_f32_e32 v80, 1.0, v99
	v_rcp_f32_e32 v80, v80
	v_add_f32_e32 v81, 1.0, v100
	v_rcp_f32_e32 v81, v81
	v_mul_f32_e32 v84, v92, v84
	v_mul_f32_e32 v80, v84, v80
	v_mul_f32_e32 v84, v93, v85
	v_mul_f32_e32 v81, v84, v81
	v_mul_f32_e32 v84, 0xbfb8aa3b, v94
	v_exp_f32_e32 v84, v84
	v_mul_f32_e32 v85, 0xbfb8aa3b, v95
	v_exp_f32_e32 v85, v85
	v_cvt_pk_bf16_f32 v80, v80, v81
	v_add_f32_e32 v81, 1.0, v84
	v_rcp_f32_e32 v81, v81
	v_add_f32_e32 v84, 1.0, v85
	v_rcp_f32_e32 v84, v84
	v_pk_mul_f32 v[86:87], v[86:87], v[166:167] op_sel_hi:[1,0]
	v_pk_mul_f32 v[88:89], v[88:89], v[166:167] op_sel_hi:[1,0]
	v_mul_f32_e32 v85, v94, v86
	v_mul_f32_e32 v81, v85, v81
	v_mul_f32_e32 v85, v95, v87
	v_mul_f32_e32 v84, v85, v84
	v_mul_f32_e32 v85, 0xbfb8aa3b, v88
	v_exp_f32_e32 v85, v85
	v_mul_f32_e32 v86, 0xbfb8aa3b, v89
	v_exp_f32_e32 v86, v86
	v_cvt_pk_bf16_f32 v81, v81, v84
	v_add_f32_e32 v84, 1.0, v85
	v_rcp_f32_e32 v84, v84
	v_add_f32_e32 v85, 1.0, v86
	v_rcp_f32_e32 v85, v85
	v_pk_mul_f32 v[90:91], v[90:91], v[166:167] op_sel_hi:[1,0]
	v_mul_f32_e32 v82, v88, v82
	v_mul_f32_e32 v82, v82, v84
	v_mul_f32_e32 v83, v89, v83
	v_mul_f32_e32 v84, 0xbfb8aa3b, v90
	v_mul_f32_e32 v83, v83, v85
	v_exp_f32_e32 v84, v84
	v_mul_f32_e32 v85, 0xbfb8aa3b, v91
	v_exp_f32_e32 v85, v85
	v_cvt_pk_bf16_f32 v82, v82, v83
	v_add_f32_e32 v83, 1.0, v84
	v_rcp_f32_e32 v83, v83
	v_add_f32_e32 v84, 1.0, v85
	v_rcp_f32_e32 v84, v84
	v_rsq_f32_e32 v148, v163
	v_mul_f32_e32 v85, v90, v96
	v_mul_f32_e32 v83, v85, v83
	v_mul_f32_e32 v85, v91, v97
	v_add_u32_e32 v98, s11, v152
	v_mul_f32_e32 v84, v85, v84
	v_cvt_pk_bf16_f32 v83, v83, v84
	v_mad_i64_i32 v[84:85], s[22:23], v98, s68, v[112:113]
	v_lshl_add_u64 v[84:85], v[84:85], 0, v[114:115]
	v_pk_mul_f32 v[76:77], v[76:77], v[148:149] op_sel_hi:[1,0]
	global_store_dwordx4 v[84:85], v[80:83], off
	v_pk_mul_f32 v[68:69], v[68:69], v[148:149] op_sel_hi:[1,0]
	v_pk_mul_f32 v[78:79], v[78:79], v[148:149] op_sel_hi:[1,0]
	v_pk_mul_f32 v[80:81], v[66:67], v[148:149] op_sel_hi:[1,0]
	v_mul_f32_e32 v66, 0xbfb8aa3b, v76
	v_exp_f32_e32 v83, v66
	v_mul_f32_e32 v66, 0xbfb8aa3b, v77
	v_exp_f32_e32 v84, v66
	v_pk_mul_f32 v[66:67], v[64:65], v[148:149] op_sel_hi:[1,0]
	v_add_f32_e32 v64, 1.0, v83
	v_rcp_f32_e32 v64, v64
	v_add_f32_e32 v65, 1.0, v84
	v_rcp_f32_e32 v65, v65
	v_mul_f32_e32 v68, v76, v68
	v_mul_f32_e32 v64, v68, v64
	v_mul_f32_e32 v68, v77, v69
	v_mul_f32_e32 v65, v68, v65
	v_mul_f32_e32 v68, 0xbfb8aa3b, v78
	v_exp_f32_e32 v68, v68
	v_mul_f32_e32 v69, 0xbfb8aa3b, v79
	v_exp_f32_e32 v69, v69
	v_cvt_pk_bf16_f32 v64, v64, v65
	v_add_f32_e32 v65, 1.0, v68
	v_rcp_f32_e32 v65, v65
	v_add_f32_e32 v68, 1.0, v69
	v_rcp_f32_e32 v68, v68
	v_pk_mul_f32 v[70:71], v[70:71], v[148:149] op_sel_hi:[1,0]
	v_pk_mul_f32 v[72:73], v[72:73], v[148:149] op_sel_hi:[1,0]
	v_mul_f32_e32 v69, v78, v70
	v_mul_f32_e32 v65, v69, v65
	v_mul_f32_e32 v69, v79, v71
	v_mul_f32_e32 v68, v69, v68
	v_mul_f32_e32 v69, 0xbfb8aa3b, v72
	v_exp_f32_e32 v69, v69
	v_mul_f32_e32 v70, 0xbfb8aa3b, v73
	v_exp_f32_e32 v70, v70
	v_cvt_pk_bf16_f32 v65, v65, v68
	v_add_f32_e32 v68, 1.0, v69
	v_rcp_f32_e32 v68, v68
	v_add_f32_e32 v69, 1.0, v70
	v_rcp_f32_e32 v69, v69
	v_pk_mul_f32 v[74:75], v[74:75], v[148:149] op_sel_hi:[1,0]
	v_mul_f32_e32 v66, v72, v66
	v_mul_f32_e32 v66, v66, v68
	v_mul_f32_e32 v67, v73, v67
	v_mul_f32_e32 v68, 0xbfb8aa3b, v74
	v_mul_f32_e32 v67, v67, v69
	v_exp_f32_e32 v68, v68
	v_mul_f32_e32 v69, 0xbfb8aa3b, v75
	v_exp_f32_e32 v69, v69
	v_cvt_pk_bf16_f32 v66, v66, v67
	v_add_f32_e32 v67, 1.0, v68
	v_rcp_f32_e32 v67, v67
	v_add_f32_e32 v68, 1.0, v69
	v_rcp_f32_e32 v68, v68
	v_mul_f32_e32 v69, v74, v80
	v_mul_f32_e32 v67, v69, v67
	v_mul_f32_e32 v69, v75, v81
	v_add_u32_e32 v82, s11, v153
	v_mul_f32_e32 v68, v69, v68
	v_cvt_pk_bf16_f32 v67, v67, v68
	v_mad_i64_i32 v[68:69], s[22:23], v82, s68, v[112:113]
	v_add_u32_e32 v88, 0x80, v146
	v_lshl_add_u64 v[68:69], v[68:69], 0, v[114:115]
	v_ashrrev_i32_e32 v89, 31, v88
	global_store_dwordx4 v[68:69], v[64:67], off
	v_add_u32_e32 v70, 0x90, v146
	v_ashrrev_i32_e32 v71, 31, v70
	v_lshlrev_b64 v[64:65], 6, v[88:89]
	v_lshl_add_u64 v[64:65], v[136:137], 0, v[64:65]
	s_waitcnt vmcnt(4)
	v_mov_b32_e32 v72, v236
	v_mov_b32_e32 v73, v237
	v_mov_b32_e32 v74, v238
	v_mov_b32_e32 v75, v239
	v_lshlrev_b64 v[64:65], 6, v[70:71]
	v_lshl_add_u64 v[64:65], v[136:137], 0, v[64:65]
	v_mov_b32_e32 v76, v240
	v_mov_b32_e32 v77, v241
	v_mov_b32_e32 v78, v242
	v_mov_b32_e32 v79, v243
	v_add_u32_e32 v66, 0xa0, v146
	v_ashrrev_i32_e32 v67, 31, v66
	v_lshlrev_b64 v[64:65], 6, v[66:67]
	v_lshl_add_u64 v[64:65], v[136:137], 0, v[64:65]
	v_mov_b32_e32 v80, v244
	v_mov_b32_e32 v81, v245
	v_mov_b32_e32 v82, v246
	v_mov_b32_e32 v83, v247
	v_add_u32_e32 v64, 0xb0, v146
	v_ashrrev_i32_e32 v65, 31, v64
	v_lshlrev_b64 v[68:69], 6, v[64:65]
	v_lshl_add_u64 v[68:69], v[136:137], 0, v[68:69]
	v_mov_b32_e32 v84, v248
	v_mov_b32_e32 v85, v249
	v_mov_b32_e32 v86, v250
	v_mov_b32_e32 v87, v251
	s_andn2_b64 vcc, exec, s[0:1]
	s_mov_b64 s[0:1], -1
	v_mov_b32_e32 v68, v73
	v_mov_b32_e32 v69, v74
	v_mov_b32_e32 v73, v75
	v_pk_add_f32 v[68:69], v[68:69], v[72:73]
	s_nop 0
	v_add_f32_e32 v65, v68, v69
	ds_bpermute_b32 v67, v160, v65
	v_mov_b32_e32 v68, v77
	v_mov_b32_e32 v69, v78
	v_mov_b32_e32 v77, v79
	v_pk_add_f32 v[68:69], v[68:69], v[76:77]
	s_waitcnt lgkmcnt(0)
	v_add_f32_e32 v65, v65, v67
	ds_bpermute_b32 v67, v147, v65
	v_add_f32_e32 v68, v68, v69
	ds_bpermute_b32 v69, v160, v68
	s_waitcnt lgkmcnt(1)
	v_add_f32_e32 v65, v65, v67
	v_fmamk_f32 v65, v65, 0x3a800000, v159
	v_rsq_f32_e32 v72, v65
	s_waitcnt lgkmcnt(0)
	v_add_f32_e32 v65, v68, v69
	v_mov_b32_e32 v68, v81
	v_mov_b32_e32 v69, v82
	v_mov_b32_e32 v81, v83
	v_pk_add_f32 v[68:69], v[68:69], v[80:81]
	ds_bpermute_b32 v67, v147, v65
	v_add_f32_e32 v71, v68, v69
	v_mov_b32_e32 v68, v85
	v_mov_b32_e32 v69, v86
	v_mov_b32_e32 v85, v87
	ds_bpermute_b32 v73, v160, v71
	v_pk_add_f32 v[68:69], v[68:69], v[84:85]
	s_waitcnt lgkmcnt(1)
	v_add_f32_e32 v65, v65, v67
	v_add_f32_e32 v68, v68, v69
	ds_bpermute_b32 v69, v160, v68
	s_waitcnt lgkmcnt(1)
	v_add_f32_e32 v67, v71, v73
	ds_bpermute_b32 v71, v147, v67
	v_fmamk_f32 v65, v65, 0x3a800000, v159
	v_rsq_f32_e32 v74, v65
	s_waitcnt lgkmcnt(1)
	v_add_f32_e32 v68, v68, v69
	ds_bpermute_b32 v69, v147, v68
	s_waitcnt lgkmcnt(1)
	v_add_f32_e32 v65, v67, v71
	v_fmamk_f32 v65, v65, 0x3a800000, v159
	v_rsq_f32_e32 v76, v65
	v_pk_mul_f32 v[60:61], v[60:61], v[72:73] op_sel_hi:[1,0]
	s_waitcnt lgkmcnt(0)
	v_add_f32_e32 v65, v68, v69
	v_fmamk_f32 v65, v65, 0x3a800000, v159
	v_pk_mul_f32 v[78:79], v[50:51], v[72:73] op_sel_hi:[1,0]
	v_mul_f32_e32 v50, 0xbfb8aa3b, v60
	v_rsq_f32_e32 v68, v65
	v_exp_f32_e32 v65, v50
	v_mul_f32_e32 v50, 0xbfb8aa3b, v61
	v_exp_f32_e32 v67, v50
	v_pk_mul_f32 v[50:51], v[48:49], v[72:73] op_sel_hi:[1,0]
	v_add_f32_e32 v48, 1.0, v65
	v_rcp_f32_e32 v48, v48
	v_add_f32_e32 v49, 1.0, v67
	v_rcp_f32_e32 v49, v49
	v_pk_mul_f32 v[52:53], v[52:53], v[72:73] op_sel_hi:[1,0]
	v_pk_mul_f32 v[62:63], v[62:63], v[72:73] op_sel_hi:[1,0]
	v_mul_f32_e32 v52, v60, v52
	v_mul_f32_e32 v48, v52, v48
	v_mul_f32_e32 v52, v61, v53
	v_mul_f32_e32 v49, v52, v49
	v_mul_f32_e32 v52, 0xbfb8aa3b, v62
	v_exp_f32_e32 v52, v52
	v_mul_f32_e32 v53, 0xbfb8aa3b, v63
	v_exp_f32_e32 v53, v53
	v_cvt_pk_bf16_f32 v48, v48, v49
	v_add_f32_e32 v49, 1.0, v52
	v_rcp_f32_e32 v49, v49
	v_add_f32_e32 v52, 1.0, v53
	v_rcp_f32_e32 v52, v52
	v_pk_mul_f32 v[54:55], v[54:55], v[72:73] op_sel_hi:[1,0]
	v_pk_mul_f32 v[56:57], v[56:57], v[72:73] op_sel_hi:[1,0]
	v_mul_f32_e32 v53, v62, v54
	v_mul_f32_e32 v49, v53, v49
	v_mul_f32_e32 v53, v63, v55
	v_mul_f32_e32 v52, v53, v52
	v_mul_f32_e32 v53, 0xbfb8aa3b, v56
	v_exp_f32_e32 v53, v53
	v_mul_f32_e32 v54, 0xbfb8aa3b, v57
	v_exp_f32_e32 v54, v54
	v_cvt_pk_bf16_f32 v49, v49, v52
	v_add_f32_e32 v52, 1.0, v53
	v_rcp_f32_e32 v52, v52
	v_add_f32_e32 v53, 1.0, v54
	v_rcp_f32_e32 v53, v53
	v_pk_mul_f32 v[58:59], v[58:59], v[72:73] op_sel_hi:[1,0]
	v_mul_f32_e32 v50, v56, v50
	v_mul_f32_e32 v50, v50, v52
	v_mul_f32_e32 v51, v57, v51
	v_mul_f32_e32 v52, 0xbfb8aa3b, v58
	v_mul_f32_e32 v51, v51, v53
	v_exp_f32_e32 v52, v52
	v_mul_f32_e32 v53, 0xbfb8aa3b, v59
	v_exp_f32_e32 v53, v53
	v_cvt_pk_bf16_f32 v50, v50, v51
	v_add_f32_e32 v51, 1.0, v52
	v_rcp_f32_e32 v51, v51
	v_add_f32_e32 v52, 1.0, v53
	v_rcp_f32_e32 v52, v52
	v_mul_f32_e32 v53, v58, v78
	v_mul_f32_e32 v51, v53, v51
	v_mul_f32_e32 v53, v59, v79
	v_mul_f32_e32 v52, v53, v52
	v_cvt_pk_bf16_f32 v51, v51, v52
	v_mad_i64_i32 v[52:53], s[22:23], v88, s68, v[112:113]
	v_lshl_add_u64 v[52:53], v[52:53], 0, v[114:115]
	v_pk_mul_f32 v[44:45], v[44:45], v[74:75] op_sel_hi:[1,0]
	global_store_dwordx4 v[52:53], v[48:51], off
	v_pk_mul_f32 v[36:37], v[36:37], v[74:75] op_sel_hi:[1,0]
	v_pk_mul_f32 v[46:47], v[46:47], v[74:75] op_sel_hi:[1,0]
	v_pk_mul_f32 v[48:49], v[34:35], v[74:75] op_sel_hi:[1,0]
	v_mul_f32_e32 v34, 0xbfb8aa3b, v44
	v_exp_f32_e32 v50, v34
	v_mul_f32_e32 v34, 0xbfb8aa3b, v45
	v_exp_f32_e32 v51, v34
	v_pk_mul_f32 v[34:35], v[32:33], v[74:75] op_sel_hi:[1,0]
	v_add_f32_e32 v32, 1.0, v50
	v_rcp_f32_e32 v32, v32
	v_add_f32_e32 v33, 1.0, v51
	v_rcp_f32_e32 v33, v33
	v_mul_f32_e32 v36, v44, v36
	v_mul_f32_e32 v32, v36, v32
	v_mul_f32_e32 v36, v45, v37
	v_mul_f32_e32 v33, v36, v33
	v_mul_f32_e32 v36, 0xbfb8aa3b, v46
	v_exp_f32_e32 v36, v36
	v_mul_f32_e32 v37, 0xbfb8aa3b, v47
	v_exp_f32_e32 v37, v37
	v_cvt_pk_bf16_f32 v32, v32, v33
	v_add_f32_e32 v33, 1.0, v36
	v_rcp_f32_e32 v33, v33
	v_add_f32_e32 v36, 1.0, v37
	v_rcp_f32_e32 v36, v36
	v_pk_mul_f32 v[38:39], v[38:39], v[74:75] op_sel_hi:[1,0]
	v_pk_mul_f32 v[40:41], v[40:41], v[74:75] op_sel_hi:[1,0]
	v_mul_f32_e32 v37, v46, v38
	v_mul_f32_e32 v33, v37, v33
	v_mul_f32_e32 v37, v47, v39
	v_mul_f32_e32 v36, v37, v36
	v_mul_f32_e32 v37, 0xbfb8aa3b, v40
	v_exp_f32_e32 v37, v37
	v_mul_f32_e32 v38, 0xbfb8aa3b, v41
	v_exp_f32_e32 v38, v38
	v_cvt_pk_bf16_f32 v33, v33, v36
	v_add_f32_e32 v36, 1.0, v37
	v_rcp_f32_e32 v36, v36
	v_add_f32_e32 v37, 1.0, v38
	v_rcp_f32_e32 v37, v37
	v_pk_mul_f32 v[42:43], v[42:43], v[74:75] op_sel_hi:[1,0]
	v_mul_f32_e32 v34, v40, v34
	v_mul_f32_e32 v34, v34, v36
	v_mul_f32_e32 v35, v41, v35
	v_mul_f32_e32 v36, 0xbfb8aa3b, v42
	v_mul_f32_e32 v35, v35, v37
	v_exp_f32_e32 v36, v36
	v_mul_f32_e32 v37, 0xbfb8aa3b, v43
	v_exp_f32_e32 v37, v37
	v_cvt_pk_bf16_f32 v34, v34, v35
	v_add_f32_e32 v35, 1.0, v36
	v_rcp_f32_e32 v35, v35
	v_add_f32_e32 v36, 1.0, v37
	v_rcp_f32_e32 v36, v36
	v_mul_f32_e32 v37, v42, v48
	v_mul_f32_e32 v35, v37, v35
	v_mul_f32_e32 v37, v43, v49
	v_mul_f32_e32 v36, v37, v36
	v_cvt_pk_bf16_f32 v35, v35, v36
	v_mad_i64_i32 v[36:37], s[22:23], v70, s68, v[112:113]
	v_lshl_add_u64 v[36:37], v[36:37], 0, v[114:115]
	v_pk_mul_f32 v[28:29], v[28:29], v[76:77] op_sel_hi:[1,0]
	global_store_dwordx4 v[36:37], v[32:35], off
	v_pk_mul_f32 v[20:21], v[20:21], v[76:77] op_sel_hi:[1,0]
	v_pk_mul_f32 v[30:31], v[30:31], v[76:77] op_sel_hi:[1,0]
	v_pk_mul_f32 v[32:33], v[18:19], v[76:77] op_sel_hi:[1,0]
	v_mul_f32_e32 v18, 0xbfb8aa3b, v28
	v_exp_f32_e32 v34, v18
	v_mul_f32_e32 v18, 0xbfb8aa3b, v29
	v_exp_f32_e32 v35, v18
	v_pk_mul_f32 v[18:19], v[16:17], v[76:77] op_sel_hi:[1,0]
	v_add_f32_e32 v16, 1.0, v34
	v_rcp_f32_e32 v16, v16
	v_add_f32_e32 v17, 1.0, v35
	v_rcp_f32_e32 v17, v17
	v_mul_f32_e32 v20, v28, v20
	v_mul_f32_e32 v16, v20, v16
	v_mul_f32_e32 v20, v29, v21
	v_mul_f32_e32 v17, v20, v17
	v_mul_f32_e32 v20, 0xbfb8aa3b, v30
	v_exp_f32_e32 v20, v20
	v_mul_f32_e32 v21, 0xbfb8aa3b, v31
	v_exp_f32_e32 v21, v21
	v_cvt_pk_bf16_f32 v16, v16, v17
	v_add_f32_e32 v17, 1.0, v20
	v_rcp_f32_e32 v17, v17
	v_add_f32_e32 v20, 1.0, v21
	v_rcp_f32_e32 v20, v20
	v_pk_mul_f32 v[22:23], v[22:23], v[76:77] op_sel_hi:[1,0]
	v_pk_mul_f32 v[24:25], v[24:25], v[76:77] op_sel_hi:[1,0]
	v_mul_f32_e32 v21, v30, v22
	v_mul_f32_e32 v17, v21, v17
	v_mul_f32_e32 v21, v31, v23
	v_mul_f32_e32 v20, v21, v20
	v_mul_f32_e32 v21, 0xbfb8aa3b, v24
	v_exp_f32_e32 v21, v21
	v_mul_f32_e32 v22, 0xbfb8aa3b, v25
	v_exp_f32_e32 v22, v22
	v_cvt_pk_bf16_f32 v17, v17, v20
	v_add_f32_e32 v20, 1.0, v21
	v_rcp_f32_e32 v20, v20
	v_add_f32_e32 v21, 1.0, v22
	v_rcp_f32_e32 v21, v21
	v_pk_mul_f32 v[26:27], v[26:27], v[76:77] op_sel_hi:[1,0]
	v_mul_f32_e32 v18, v24, v18
	v_mul_f32_e32 v18, v18, v20
	v_mul_f32_e32 v19, v25, v19
	v_mul_f32_e32 v20, 0xbfb8aa3b, v26
	v_mul_f32_e32 v19, v19, v21
	v_exp_f32_e32 v20, v20
	v_mul_f32_e32 v21, 0xbfb8aa3b, v27
	v_exp_f32_e32 v21, v21
	v_cvt_pk_bf16_f32 v18, v18, v19
	v_add_f32_e32 v19, 1.0, v20
	v_rcp_f32_e32 v19, v19
	v_add_f32_e32 v20, 1.0, v21
	v_rcp_f32_e32 v20, v20
	v_mul_f32_e32 v21, v26, v32
	v_mul_f32_e32 v19, v21, v19
	v_mul_f32_e32 v21, v27, v33
	v_mul_f32_e32 v20, v21, v20
	v_cvt_pk_bf16_f32 v19, v19, v20
	v_mad_i64_i32 v[20:21], s[22:23], v66, s68, v[112:113]
	v_lshl_add_u64 v[20:21], v[20:21], 0, v[114:115]
	v_pk_mul_f32 v[12:13], v[12:13], v[68:69] op_sel_hi:[1,0]
	global_store_dwordx4 v[20:21], v[16:19], off
	v_pk_mul_f32 v[4:5], v[4:5], v[68:69] op_sel_hi:[1,0]
	v_pk_mul_f32 v[14:15], v[14:15], v[68:69] op_sel_hi:[1,0]
	v_pk_mul_f32 v[16:17], v[2:3], v[68:69] op_sel_hi:[1,0]
	v_mul_f32_e32 v2, 0xbfb8aa3b, v12
	v_exp_f32_e32 v18, v2
	v_mul_f32_e32 v2, 0xbfb8aa3b, v13
	v_exp_f32_e32 v19, v2
	v_pk_mul_f32 v[2:3], v[0:1], v[68:69] op_sel_hi:[1,0]
	v_add_f32_e32 v0, 1.0, v18
	v_rcp_f32_e32 v0, v0
	v_add_f32_e32 v1, 1.0, v19
	v_rcp_f32_e32 v1, v1
	v_mul_f32_e32 v4, v12, v4
	v_mul_f32_e32 v0, v4, v0
	v_mul_f32_e32 v4, v13, v5
	v_mul_f32_e32 v1, v4, v1
	v_mul_f32_e32 v4, 0xbfb8aa3b, v14
	v_exp_f32_e32 v4, v4
	v_mul_f32_e32 v5, 0xbfb8aa3b, v15
	v_exp_f32_e32 v5, v5
	v_cvt_pk_bf16_f32 v0, v0, v1
	v_add_f32_e32 v1, 1.0, v4
	v_rcp_f32_e32 v1, v1
	v_add_f32_e32 v4, 1.0, v5
	v_rcp_f32_e32 v4, v4
	v_pk_mul_f32 v[6:7], v[6:7], v[68:69] op_sel_hi:[1,0]
	v_pk_mul_f32 v[8:9], v[8:9], v[68:69] op_sel_hi:[1,0]
	v_mul_f32_e32 v5, v14, v6
	v_mul_f32_e32 v1, v5, v1
	v_mul_f32_e32 v5, v15, v7
	v_mul_f32_e32 v4, v5, v4
	v_mul_f32_e32 v5, 0xbfb8aa3b, v8
	v_exp_f32_e32 v5, v5
	v_mul_f32_e32 v6, 0xbfb8aa3b, v9
	v_exp_f32_e32 v6, v6
	v_cvt_pk_bf16_f32 v1, v1, v4
	v_add_f32_e32 v4, 1.0, v5
	v_rcp_f32_e32 v4, v4
	v_add_f32_e32 v5, 1.0, v6
	v_rcp_f32_e32 v5, v5
	v_pk_mul_f32 v[10:11], v[10:11], v[68:69] op_sel_hi:[1,0]
	v_mul_f32_e32 v2, v8, v2
	v_mul_f32_e32 v2, v2, v4
	v_mul_f32_e32 v3, v9, v3
	v_mul_f32_e32 v4, 0xbfb8aa3b, v10
	v_mul_f32_e32 v3, v3, v5
	v_exp_f32_e32 v4, v4
	v_mul_f32_e32 v5, 0xbfb8aa3b, v11
	v_exp_f32_e32 v5, v5
	v_cvt_pk_bf16_f32 v2, v2, v3
	v_add_f32_e32 v3, 1.0, v4
	v_rcp_f32_e32 v3, v3
	v_add_f32_e32 v4, 1.0, v5
	v_rcp_f32_e32 v4, v4
	v_mul_f32_e32 v5, v10, v16
	v_mul_f32_e32 v3, v5, v3
	v_mul_f32_e32 v5, v11, v17
	v_mul_f32_e32 v4, v5, v4
	v_cvt_pk_bf16_f32 v3, v3, v4
	v_mad_i64_i32 v[4:5], s[22:23], v64, s68, v[112:113]
	v_lshl_add_u64 v[4:5], v[4:5], 0, v[114:115]
	global_store_dwordx4 v[4:5], v[0:3], off
	s_cbranch_vccnz .LBB0_875
	s_andn2_b64 vcc, exec, s[4:5]
	s_cbranch_vccnz .LBB0_874
	s_barrier
	s_branch .LBB0_874

.LBB0_2126:
	s_lshl_b32 s11, s18, 8
	v_add_u32_e32 v146, s11, v149
	v_or_b32_e32 v162, 16, v146
	v_ashrrev_i32_e32 v147, 31, v146
	v_ashrrev_i32_e32 v163, 31, v162
	v_lshlrev_b64 v[160:161], 6, v[146:147]
	v_lshlrev_b64 v[162:163], 6, v[162:163]
	v_lshl_add_u64 v[160:161], v[136:137], 0, v[160:161]
	v_lshl_add_u64 v[166:167], v[136:137], 0, v[162:163]
	v_mov_b32_e32 v162, v236
	v_mov_b32_e32 v163, v237
	v_mov_b32_e32 v164, v238
	v_mov_b32_e32 v165, v239
	v_mov_b32_e32 v166, v240
	v_mov_b32_e32 v167, v241
	v_mov_b32_e32 v168, v242
	v_mov_b32_e32 v169, v243
	v_or_b32_e32 v160, 32, v146
	v_ashrrev_i32_e32 v161, 31, v160
	v_lshlrev_b64 v[160:161], 6, v[160:161]
	v_lshl_add_u64 v[160:161], v[136:137], 0, v[160:161]
	v_mov_b32_e32 v170, v244
	v_mov_b32_e32 v171, v245
	v_mov_b32_e32 v172, v246
	v_mov_b32_e32 v173, v247
	v_or_b32_e32 v160, 48, v146
	v_ashrrev_i32_e32 v161, 31, v160
	v_lshlrev_b64 v[160:161], 6, v[160:161]
	v_lshl_add_u64 v[160:161], v[136:137], 0, v[160:161]
	v_mov_b32_e32 v174, v248
	v_mov_b32_e32 v175, v249
	v_mov_b32_e32 v176, v250
	v_mov_b32_e32 v177, v251
	v_add_u32_e32 v252, 0x80, v146
	v_mov_b32_e32 v253, 0
	v_lshlrev_b64 v[252:253], 6, v[252:253]
	v_lshl_add_u64 v[252:253], v[136:137], 0, v[252:253]
	global_load_dwordx4 v[236:239], v[252:253], off
	global_load_dwordx4 v[240:243], v[252:253], off offset:1024
	global_load_dwordx4 v[244:247], v[252:253], off offset:2048
	global_load_dwordx4 v[248:251], v[252:253], off offset:3072
	v_and_b32_e32 v148, 64, v158
	v_xor_b32_e32 v147, 16, v158
	v_add_u32_e32 v148, 64, v148
	v_xor_b32_e32 v160, 32, v158
	v_cmp_lt_i32_e32 vcc, v147, v148
	v_lshl_or_b32 v178, s49, 7, v154
	v_ashrrev_i32_e32 v179, 31, v178
	v_cndmask_b32_e32 v147, v158, v147, vcc
	v_cmp_lt_i32_e32 vcc, v160, v148
	v_mov_b32_e32 v180, v163
	v_mov_b32_e32 v181, v164
	v_mov_b32_e32 v163, v165
	v_cndmask_b32_e32 v148, v158, v160, vcc
	v_pk_add_f32 v[162:163], v[180:181], v[162:163]
	v_lshlrev_b32_e32 v160, 2, v147
	v_lshlrev_b32_e32 v147, 2, v148
	v_mov_b32_e32 v164, v167
	v_mov_b32_e32 v165, v168
	v_mov_b32_e32 v167, v169
	v_add_f32_e32 v148, v162, v163
	v_mov_b32_e32 v168, v171
	v_mov_b32_e32 v169, v172
	v_mov_b32_e32 v171, v173
	v_pk_add_f32 v[162:163], v[164:165], v[166:167]
	ds_bpermute_b32 v161, v160, v148
	v_mov_b32_e32 v172, v175
	v_mov_b32_e32 v173, v176
	v_mov_b32_e32 v175, v177
	v_pk_add_f32 v[164:165], v[168:169], v[170:171]
	v_add_f32_e32 v162, v162, v163
	v_pk_add_f32 v[166:167], v[172:173], v[174:175]
	v_add_f32_e32 v163, v164, v165
	ds_bpermute_b32 v165, v160, v162
	v_add_f32_e32 v164, v166, v167
	ds_bpermute_b32 v166, v160, v163
	ds_bpermute_b32 v167, v160, v164
	s_waitcnt lgkmcnt(3)
	v_add_f32_e32 v148, v148, v161
	ds_bpermute_b32 v161, v147, v148
	s_waitcnt lgkmcnt(3)
	v_add_f32_e32 v162, v162, v165
	ds_bpermute_b32 v165, v147, v162
	s_waitcnt lgkmcnt(3)
	v_add_f32_e32 v163, v163, v166
	s_waitcnt lgkmcnt(2)
	v_add_f32_e32 v164, v164, v167
	ds_bpermute_b32 v166, v147, v163
	ds_bpermute_b32 v167, v147, v164
	s_waitcnt lgkmcnt(3)
	v_add_f32_e32 v148, v148, v161
	v_fmamk_f32 v148, v148, 0x3a800000, v159
	s_waitcnt lgkmcnt(2)
	v_add_f32_e32 v161, v162, v165
	v_rsq_f32_e32 v162, v148
	s_waitcnt lgkmcnt(1)
	v_add_f32_e32 v163, v163, v166
	s_waitcnt lgkmcnt(0)
	v_add_f32_e32 v164, v164, v167
	v_fmamk_f32 v148, v161, 0x3a800000, v159
	v_fmamk_f32 v161, v163, 0x3a800000, v159
	v_fmamk_f32 v163, v164, 0x3a800000, v159
	v_pk_mul_f32 v[126:127], v[126:127], v[162:163] op_sel_hi:[1,0]
	v_pk_mul_f32 v[124:125], v[124:125], v[162:163] op_sel_hi:[1,0]
	v_pk_mul_f32 v[118:119], v[118:119], v[162:163] op_sel_hi:[1,0]
	v_pk_mul_f32 v[116:117], v[116:117], v[162:163] op_sel_hi:[1,0]
	v_mul_f32_e32 v118, v126, v118
	v_mul_f32_e32 v116, v124, v116
	v_mul_f32_e32 v124, 0xbfb8aa3b, v124
	v_mul_f32_e32 v117, v125, v117
	v_mul_f32_e32 v125, 0xbfb8aa3b, v125
	v_mul_f32_e32 v126, 0xbfb8aa3b, v126
	v_mul_f32_e32 v119, v127, v119
	v_mul_f32_e32 v127, 0xbfb8aa3b, v127
	v_exp_f32_e32 v124, v124
	v_exp_f32_e32 v125, v125
	v_exp_f32_e32 v126, v126
	v_exp_f32_e32 v127, v127
	v_pk_mul_f32 v[120:121], v[120:121], v[162:163] op_sel_hi:[1,0]
	v_pk_mul_f32 v[122:123], v[122:123], v[162:163] op_sel_hi:[1,0]
	v_pk_mul_f32 v[114:115], v[114:115], v[162:163] op_sel_hi:[1,0]
	v_pk_mul_f32 v[112:113], v[112:113], v[162:163] op_sel_hi:[1,0]
	v_mul_f32_e32 v162, 0xbfb8aa3b, v121
	v_add_f32_e32 v124, 1.0, v124
	v_add_f32_e32 v125, 1.0, v125
	v_add_f32_e32 v126, 1.0, v126
	v_exp_f32_e32 v162, v162
	v_add_f32_e32 v127, 1.0, v127
	v_rcp_f32_e32 v124, v124
	v_rcp_f32_e32 v125, v125
	v_rcp_f32_e32 v126, v126
	v_rcp_f32_e32 v127, v127
	v_rsq_f32_e32 v166, v161
	v_mul_f32_e32 v161, 0xbfb8aa3b, v120
	v_exp_f32_e32 v161, v161
	v_add_f32_e32 v162, 1.0, v162
	v_mul_f32_e32 v116, v116, v124
	v_mul_f32_e32 v117, v117, v125
	v_mul_f32_e32 v118, v118, v126
	v_mul_f32_e32 v119, v119, v127
	v_cvt_pk_bf16_f32 v116, v116, v117
	v_cvt_pk_bf16_f32 v117, v118, v119
	v_rcp_f32_e32 v118, v162
	v_add_f32_e32 v161, 1.0, v161
	v_mul_f32_e32 v113, v121, v113
	v_rcp_f32_e32 v161, v161
	v_mul_f32_e32 v113, v113, v118
	v_mul_f32_e32 v118, 0xbfb8aa3b, v122
	v_exp_f32_e32 v119, v118
	v_mul_f32_e32 v118, 0xbfb8aa3b, v123
	v_mul_f32_e32 v112, v120, v112
	v_exp_f32_e32 v120, v118
	v_mul_f32_e32 v112, v112, v161
	v_cvt_pk_bf16_f32 v118, v112, v113
	v_add_f32_e32 v112, 1.0, v119
	v_rcp_f32_e32 v112, v112
	v_add_f32_e32 v113, 1.0, v120
	v_rcp_f32_e32 v113, v113
	v_mul_f32_e32 v114, v122, v114
	v_rsq_f32_e32 v164, v148
	v_mul_f32_e32 v112, v114, v112
	v_mul_f32_e32 v114, v123, v115
	v_mul_f32_e32 v113, v114, v113
	v_cvt_pk_bf16_f32 v119, v112, v113
	v_mov_b64_e32 v[112:113], s[36:37]
	v_mad_i64_i32 v[120:121], s[20:21], v146, s48, v[112:113]
	v_lshlrev_b64 v[114:115], 1, v[178:179]
	v_lshl_add_u64 v[120:121], v[120:121], 0, v[114:115]
	v_pk_mul_f32 v[108:109], v[108:109], v[164:165] op_sel_hi:[1,0]
	global_store_dwordx4 v[120:121], v[116:119], off
	v_pk_mul_f32 v[100:101], v[100:101], v[164:165] op_sel_hi:[1,0]
	v_pk_mul_f32 v[110:111], v[110:111], v[164:165] op_sel_hi:[1,0]
	v_pk_mul_f32 v[116:117], v[98:99], v[164:165] op_sel_hi:[1,0]
	v_mul_f32_e32 v98, 0xbfb8aa3b, v108
	v_exp_f32_e32 v119, v98
	v_mul_f32_e32 v98, 0xbfb8aa3b, v109
	v_exp_f32_e32 v120, v98
	v_pk_mul_f32 v[98:99], v[96:97], v[164:165] op_sel_hi:[1,0]
	v_add_f32_e32 v96, 1.0, v119
	v_rcp_f32_e32 v96, v96
	v_add_f32_e32 v97, 1.0, v120
	v_rcp_f32_e32 v97, v97
	v_mul_f32_e32 v100, v108, v100
	v_mul_f32_e32 v96, v100, v96
	v_mul_f32_e32 v100, v109, v101
	v_mul_f32_e32 v97, v100, v97
	v_mul_f32_e32 v100, 0xbfb8aa3b, v110
	v_exp_f32_e32 v100, v100
	v_mul_f32_e32 v101, 0xbfb8aa3b, v111
	v_exp_f32_e32 v101, v101
	v_cvt_pk_bf16_f32 v96, v96, v97
	v_add_f32_e32 v97, 1.0, v100
	v_rcp_f32_e32 v97, v97
	v_add_f32_e32 v100, 1.0, v101
	v_rcp_f32_e32 v100, v100
	v_pk_mul_f32 v[102:103], v[102:103], v[164:165] op_sel_hi:[1,0]
	v_pk_mul_f32 v[104:105], v[104:105], v[164:165] op_sel_hi:[1,0]
	v_mul_f32_e32 v101, v110, v102
	v_mul_f32_e32 v97, v101, v97
	v_mul_f32_e32 v101, v111, v103
	v_mul_f32_e32 v100, v101, v100
	v_mul_f32_e32 v101, 0xbfb8aa3b, v104
	v_exp_f32_e32 v101, v101
	v_mul_f32_e32 v102, 0xbfb8aa3b, v105
	v_exp_f32_e32 v102, v102
	v_cvt_pk_bf16_f32 v97, v97, v100
	v_add_f32_e32 v100, 1.0, v101
	v_rcp_f32_e32 v100, v100
	v_add_f32_e32 v101, 1.0, v102
	v_rcp_f32_e32 v101, v101
	v_pk_mul_f32 v[106:107], v[106:107], v[164:165] op_sel_hi:[1,0]
	v_mul_f32_e32 v98, v104, v98
	v_mul_f32_e32 v98, v98, v100
	v_mul_f32_e32 v99, v105, v99
	v_mul_f32_e32 v100, 0xbfb8aa3b, v106
	v_mul_f32_e32 v99, v99, v101
	v_exp_f32_e32 v100, v100
	v_mul_f32_e32 v101, 0xbfb8aa3b, v107
	v_exp_f32_e32 v101, v101
	v_cvt_pk_bf16_f32 v98, v98, v99
	v_add_f32_e32 v99, 1.0, v100
	v_rcp_f32_e32 v99, v99
	v_add_f32_e32 v100, 1.0, v101
	v_rcp_f32_e32 v100, v100
	v_mul_f32_e32 v101, v106, v116
	v_mul_f32_e32 v99, v101, v99
	v_mul_f32_e32 v101, v107, v117
	v_add_u32_e32 v118, s11, v151
	v_mul_f32_e32 v100, v101, v100
	v_cvt_pk_bf16_f32 v99, v99, v100
	v_mad_i64_i32 v[100:101], s[20:21], v118, s48, v[112:113]
	v_lshl_add_u64 v[100:101], v[100:101], 0, v[114:115]
	v_pk_mul_f32 v[92:93], v[92:93], v[166:167] op_sel_hi:[1,0]
	global_store_dwordx4 v[100:101], v[96:99], off
	v_pk_mul_f32 v[84:85], v[84:85], v[166:167] op_sel_hi:[1,0]
	v_pk_mul_f32 v[94:95], v[94:95], v[166:167] op_sel_hi:[1,0]
	v_pk_mul_f32 v[96:97], v[82:83], v[166:167] op_sel_hi:[1,0]
	v_mul_f32_e32 v82, 0xbfb8aa3b, v92
	v_exp_f32_e32 v99, v82
	v_mul_f32_e32 v82, 0xbfb8aa3b, v93
	v_exp_f32_e32 v100, v82
	v_pk_mul_f32 v[82:83], v[80:81], v[166:167] op_sel_hi:[1,0]
	v_add_f32_e32 v80, 1.0, v99
	v_rcp_f32_e32 v80, v80
	v_add_f32_e32 v81, 1.0, v100
	v_rcp_f32_e32 v81, v81
	v_mul_f32_e32 v84, v92, v84
	v_mul_f32_e32 v80, v84, v80
	v_mul_f32_e32 v84, v93, v85
	v_mul_f32_e32 v81, v84, v81
	v_mul_f32_e32 v84, 0xbfb8aa3b, v94
	v_exp_f32_e32 v84, v84
	v_mul_f32_e32 v85, 0xbfb8aa3b, v95
	v_exp_f32_e32 v85, v85
	v_cvt_pk_bf16_f32 v80, v80, v81
	v_add_f32_e32 v81, 1.0, v84
	v_rcp_f32_e32 v81, v81
	v_add_f32_e32 v84, 1.0, v85
	v_rcp_f32_e32 v84, v84
	v_pk_mul_f32 v[86:87], v[86:87], v[166:167] op_sel_hi:[1,0]
	v_pk_mul_f32 v[88:89], v[88:89], v[166:167] op_sel_hi:[1,0]
	v_mul_f32_e32 v85, v94, v86
	v_mul_f32_e32 v81, v85, v81
	v_mul_f32_e32 v85, v95, v87
	v_mul_f32_e32 v84, v85, v84
	v_mul_f32_e32 v85, 0xbfb8aa3b, v88
	v_exp_f32_e32 v85, v85
	v_mul_f32_e32 v86, 0xbfb8aa3b, v89
	v_exp_f32_e32 v86, v86
	v_cvt_pk_bf16_f32 v81, v81, v84
	v_add_f32_e32 v84, 1.0, v85
	v_rcp_f32_e32 v84, v84
	v_add_f32_e32 v85, 1.0, v86
	v_rcp_f32_e32 v85, v85
	v_pk_mul_f32 v[90:91], v[90:91], v[166:167] op_sel_hi:[1,0]
	v_mul_f32_e32 v82, v88, v82
	v_mul_f32_e32 v82, v82, v84
	v_mul_f32_e32 v83, v89, v83
	v_mul_f32_e32 v84, 0xbfb8aa3b, v90
	v_mul_f32_e32 v83, v83, v85
	v_exp_f32_e32 v84, v84
	v_mul_f32_e32 v85, 0xbfb8aa3b, v91
	v_exp_f32_e32 v85, v85
	v_cvt_pk_bf16_f32 v82, v82, v83
	v_add_f32_e32 v83, 1.0, v84
	v_rcp_f32_e32 v83, v83
	v_add_f32_e32 v84, 1.0, v85
	v_rcp_f32_e32 v84, v84
	v_rsq_f32_e32 v148, v163
	v_mul_f32_e32 v85, v90, v96
	v_mul_f32_e32 v83, v85, v83
	v_mul_f32_e32 v85, v91, v97
	v_add_u32_e32 v98, s11, v152
	v_mul_f32_e32 v84, v85, v84
	v_cvt_pk_bf16_f32 v83, v83, v84
	v_mad_i64_i32 v[84:85], s[20:21], v98, s48, v[112:113]
	v_lshl_add_u64 v[84:85], v[84:85], 0, v[114:115]
	v_pk_mul_f32 v[76:77], v[76:77], v[148:149] op_sel_hi:[1,0]
	global_store_dwordx4 v[84:85], v[80:83], off
	v_pk_mul_f32 v[68:69], v[68:69], v[148:149] op_sel_hi:[1,0]
	v_pk_mul_f32 v[78:79], v[78:79], v[148:149] op_sel_hi:[1,0]
	v_pk_mul_f32 v[80:81], v[66:67], v[148:149] op_sel_hi:[1,0]
	v_mul_f32_e32 v66, 0xbfb8aa3b, v76
	v_exp_f32_e32 v83, v66
	v_mul_f32_e32 v66, 0xbfb8aa3b, v77
	v_exp_f32_e32 v84, v66
	v_pk_mul_f32 v[66:67], v[64:65], v[148:149] op_sel_hi:[1,0]
	v_add_f32_e32 v64, 1.0, v83
	v_rcp_f32_e32 v64, v64
	v_add_f32_e32 v65, 1.0, v84
	v_rcp_f32_e32 v65, v65
	v_mul_f32_e32 v68, v76, v68
	v_mul_f32_e32 v64, v68, v64
	v_mul_f32_e32 v68, v77, v69
	v_mul_f32_e32 v65, v68, v65
	v_mul_f32_e32 v68, 0xbfb8aa3b, v78
	v_exp_f32_e32 v68, v68
	v_mul_f32_e32 v69, 0xbfb8aa3b, v79
	v_exp_f32_e32 v69, v69
	v_cvt_pk_bf16_f32 v64, v64, v65
	v_add_f32_e32 v65, 1.0, v68
	v_rcp_f32_e32 v65, v65
	v_add_f32_e32 v68, 1.0, v69
	v_rcp_f32_e32 v68, v68
	v_pk_mul_f32 v[70:71], v[70:71], v[148:149] op_sel_hi:[1,0]
	v_pk_mul_f32 v[72:73], v[72:73], v[148:149] op_sel_hi:[1,0]
	v_mul_f32_e32 v69, v78, v70
	v_mul_f32_e32 v65, v69, v65
	v_mul_f32_e32 v69, v79, v71
	v_mul_f32_e32 v68, v69, v68
	v_mul_f32_e32 v69, 0xbfb8aa3b, v72
	v_exp_f32_e32 v69, v69
	v_mul_f32_e32 v70, 0xbfb8aa3b, v73
	v_exp_f32_e32 v70, v70
	v_cvt_pk_bf16_f32 v65, v65, v68
	v_add_f32_e32 v68, 1.0, v69
	v_rcp_f32_e32 v68, v68
	v_add_f32_e32 v69, 1.0, v70
	v_rcp_f32_e32 v69, v69
	v_pk_mul_f32 v[74:75], v[74:75], v[148:149] op_sel_hi:[1,0]
	v_mul_f32_e32 v66, v72, v66
	v_mul_f32_e32 v66, v66, v68
	v_mul_f32_e32 v67, v73, v67
	v_mul_f32_e32 v68, 0xbfb8aa3b, v74
	v_mul_f32_e32 v67, v67, v69
	v_exp_f32_e32 v68, v68
	v_mul_f32_e32 v69, 0xbfb8aa3b, v75
	v_exp_f32_e32 v69, v69
	v_cvt_pk_bf16_f32 v66, v66, v67
	v_add_f32_e32 v67, 1.0, v68
	v_rcp_f32_e32 v67, v67
	v_add_f32_e32 v68, 1.0, v69
	v_rcp_f32_e32 v68, v68
	v_mul_f32_e32 v69, v74, v80
	v_mul_f32_e32 v67, v69, v67
	v_mul_f32_e32 v69, v75, v81
	v_add_u32_e32 v82, s11, v153
	v_mul_f32_e32 v68, v69, v68
	v_cvt_pk_bf16_f32 v67, v67, v68
	v_mad_i64_i32 v[68:69], s[20:21], v82, s48, v[112:113]
	v_add_u32_e32 v88, 0x80, v146
	v_lshl_add_u64 v[68:69], v[68:69], 0, v[114:115]
	v_ashrrev_i32_e32 v89, 31, v88
	global_store_dwordx4 v[68:69], v[64:67], off
	v_add_u32_e32 v70, 0x90, v146
	v_ashrrev_i32_e32 v71, 31, v70
	v_lshlrev_b64 v[64:65], 6, v[88:89]
	v_lshl_add_u64 v[64:65], v[136:137], 0, v[64:65]
	s_waitcnt vmcnt(4)
	v_mov_b32_e32 v72, v236
	v_mov_b32_e32 v73, v237
	v_mov_b32_e32 v74, v238
	v_mov_b32_e32 v75, v239
	v_lshlrev_b64 v[64:65], 6, v[70:71]
	v_lshl_add_u64 v[64:65], v[136:137], 0, v[64:65]
	v_mov_b32_e32 v76, v240
	v_mov_b32_e32 v77, v241
	v_mov_b32_e32 v78, v242
	v_mov_b32_e32 v79, v243
	v_add_u32_e32 v66, 0xa0, v146
	v_ashrrev_i32_e32 v67, 31, v66
	v_lshlrev_b64 v[64:65], 6, v[66:67]
	v_lshl_add_u64 v[64:65], v[136:137], 0, v[64:65]
	v_mov_b32_e32 v80, v244
	v_mov_b32_e32 v81, v245
	v_mov_b32_e32 v82, v246
	v_mov_b32_e32 v83, v247
	v_add_u32_e32 v64, 0xb0, v146
	v_ashrrev_i32_e32 v65, 31, v64
	v_lshlrev_b64 v[68:69], 6, v[64:65]
	v_lshl_add_u64 v[68:69], v[136:137], 0, v[68:69]
	v_mov_b32_e32 v84, v248
	v_mov_b32_e32 v85, v249
	v_mov_b32_e32 v86, v250
	v_mov_b32_e32 v87, v251
	s_andn2_b64 vcc, exec, s[0:1]
	s_mov_b64 s[0:1], -1
	v_mov_b32_e32 v68, v73
	v_mov_b32_e32 v69, v74
	v_mov_b32_e32 v73, v75
	v_pk_add_f32 v[68:69], v[68:69], v[72:73]
	s_nop 0
	v_add_f32_e32 v65, v68, v69
	ds_bpermute_b32 v67, v160, v65
	v_mov_b32_e32 v68, v77
	v_mov_b32_e32 v69, v78
	v_mov_b32_e32 v77, v79
	v_pk_add_f32 v[68:69], v[68:69], v[76:77]
	s_waitcnt lgkmcnt(0)
	v_add_f32_e32 v65, v65, v67
	ds_bpermute_b32 v67, v147, v65
	v_add_f32_e32 v68, v68, v69
	ds_bpermute_b32 v69, v160, v68
	s_waitcnt lgkmcnt(1)
	v_add_f32_e32 v65, v65, v67
	v_fmamk_f32 v65, v65, 0x3a800000, v159
	v_rsq_f32_e32 v72, v65
	s_waitcnt lgkmcnt(0)
	v_add_f32_e32 v65, v68, v69
	v_mov_b32_e32 v68, v81
	v_mov_b32_e32 v69, v82
	v_mov_b32_e32 v81, v83
	v_pk_add_f32 v[68:69], v[68:69], v[80:81]
	ds_bpermute_b32 v67, v147, v65
	v_add_f32_e32 v71, v68, v69
	v_mov_b32_e32 v68, v85
	v_mov_b32_e32 v69, v86
	v_mov_b32_e32 v85, v87
	ds_bpermute_b32 v73, v160, v71
	v_pk_add_f32 v[68:69], v[68:69], v[84:85]
	s_waitcnt lgkmcnt(1)
	v_add_f32_e32 v65, v65, v67
	v_add_f32_e32 v68, v68, v69
	ds_bpermute_b32 v69, v160, v68
	s_waitcnt lgkmcnt(1)
	v_add_f32_e32 v67, v71, v73
	ds_bpermute_b32 v71, v147, v67
	v_fmamk_f32 v65, v65, 0x3a800000, v159
	v_rsq_f32_e32 v74, v65
	s_waitcnt lgkmcnt(1)
	v_add_f32_e32 v68, v68, v69
	ds_bpermute_b32 v69, v147, v68
	s_waitcnt lgkmcnt(1)
	v_add_f32_e32 v65, v67, v71
	v_fmamk_f32 v65, v65, 0x3a800000, v159
	v_rsq_f32_e32 v76, v65
	v_pk_mul_f32 v[60:61], v[60:61], v[72:73] op_sel_hi:[1,0]
	s_waitcnt lgkmcnt(0)
	v_add_f32_e32 v65, v68, v69
	v_fmamk_f32 v65, v65, 0x3a800000, v159
	v_pk_mul_f32 v[78:79], v[50:51], v[72:73] op_sel_hi:[1,0]
	v_mul_f32_e32 v50, 0xbfb8aa3b, v60
	v_rsq_f32_e32 v68, v65
	v_exp_f32_e32 v65, v50
	v_mul_f32_e32 v50, 0xbfb8aa3b, v61
	v_exp_f32_e32 v67, v50
	v_pk_mul_f32 v[50:51], v[48:49], v[72:73] op_sel_hi:[1,0]
	v_add_f32_e32 v48, 1.0, v65
	v_rcp_f32_e32 v48, v48
	v_add_f32_e32 v49, 1.0, v67
	v_rcp_f32_e32 v49, v49
	v_pk_mul_f32 v[52:53], v[52:53], v[72:73] op_sel_hi:[1,0]
	v_pk_mul_f32 v[62:63], v[62:63], v[72:73] op_sel_hi:[1,0]
	v_mul_f32_e32 v52, v60, v52
	v_mul_f32_e32 v48, v52, v48
	v_mul_f32_e32 v52, v61, v53
	v_mul_f32_e32 v49, v52, v49
	v_mul_f32_e32 v52, 0xbfb8aa3b, v62
	v_exp_f32_e32 v52, v52
	v_mul_f32_e32 v53, 0xbfb8aa3b, v63
	v_exp_f32_e32 v53, v53
	v_cvt_pk_bf16_f32 v48, v48, v49
	v_add_f32_e32 v49, 1.0, v52
	v_rcp_f32_e32 v49, v49
	v_add_f32_e32 v52, 1.0, v53
	v_rcp_f32_e32 v52, v52
	v_pk_mul_f32 v[54:55], v[54:55], v[72:73] op_sel_hi:[1,0]
	v_pk_mul_f32 v[56:57], v[56:57], v[72:73] op_sel_hi:[1,0]
	v_mul_f32_e32 v53, v62, v54
	v_mul_f32_e32 v49, v53, v49
	v_mul_f32_e32 v53, v63, v55
	v_mul_f32_e32 v52, v53, v52
	v_mul_f32_e32 v53, 0xbfb8aa3b, v56
	v_exp_f32_e32 v53, v53
	v_mul_f32_e32 v54, 0xbfb8aa3b, v57
	v_exp_f32_e32 v54, v54
	v_cvt_pk_bf16_f32 v49, v49, v52
	v_add_f32_e32 v52, 1.0, v53
	v_rcp_f32_e32 v52, v52
	v_add_f32_e32 v53, 1.0, v54
	v_rcp_f32_e32 v53, v53
	v_pk_mul_f32 v[58:59], v[58:59], v[72:73] op_sel_hi:[1,0]
	v_mul_f32_e32 v50, v56, v50
	v_mul_f32_e32 v50, v50, v52
	v_mul_f32_e32 v51, v57, v51
	v_mul_f32_e32 v52, 0xbfb8aa3b, v58
	v_mul_f32_e32 v51, v51, v53
	v_exp_f32_e32 v52, v52
	v_mul_f32_e32 v53, 0xbfb8aa3b, v59
	v_exp_f32_e32 v53, v53
	v_cvt_pk_bf16_f32 v50, v50, v51
	v_add_f32_e32 v51, 1.0, v52
	v_rcp_f32_e32 v51, v51
	v_add_f32_e32 v52, 1.0, v53
	v_rcp_f32_e32 v52, v52
	v_mul_f32_e32 v53, v58, v78
	v_mul_f32_e32 v51, v53, v51
	v_mul_f32_e32 v53, v59, v79
	v_mul_f32_e32 v52, v53, v52
	v_cvt_pk_bf16_f32 v51, v51, v52
	v_mad_i64_i32 v[52:53], s[20:21], v88, s48, v[112:113]
	v_lshl_add_u64 v[52:53], v[52:53], 0, v[114:115]
	v_pk_mul_f32 v[44:45], v[44:45], v[74:75] op_sel_hi:[1,0]
	global_store_dwordx4 v[52:53], v[48:51], off
	v_pk_mul_f32 v[36:37], v[36:37], v[74:75] op_sel_hi:[1,0]
	v_pk_mul_f32 v[46:47], v[46:47], v[74:75] op_sel_hi:[1,0]
	v_pk_mul_f32 v[48:49], v[34:35], v[74:75] op_sel_hi:[1,0]
	v_mul_f32_e32 v34, 0xbfb8aa3b, v44
	v_exp_f32_e32 v50, v34
	v_mul_f32_e32 v34, 0xbfb8aa3b, v45
	v_exp_f32_e32 v51, v34
	v_pk_mul_f32 v[34:35], v[32:33], v[74:75] op_sel_hi:[1,0]
	v_add_f32_e32 v32, 1.0, v50
	v_rcp_f32_e32 v32, v32
	v_add_f32_e32 v33, 1.0, v51
	v_rcp_f32_e32 v33, v33
	v_mul_f32_e32 v36, v44, v36
	v_mul_f32_e32 v32, v36, v32
	v_mul_f32_e32 v36, v45, v37
	v_mul_f32_e32 v33, v36, v33
	v_mul_f32_e32 v36, 0xbfb8aa3b, v46
	v_exp_f32_e32 v36, v36
	v_mul_f32_e32 v37, 0xbfb8aa3b, v47
	v_exp_f32_e32 v37, v37
	v_cvt_pk_bf16_f32 v32, v32, v33
	v_add_f32_e32 v33, 1.0, v36
	v_rcp_f32_e32 v33, v33
	v_add_f32_e32 v36, 1.0, v37
	v_rcp_f32_e32 v36, v36
	v_pk_mul_f32 v[38:39], v[38:39], v[74:75] op_sel_hi:[1,0]
	v_pk_mul_f32 v[40:41], v[40:41], v[74:75] op_sel_hi:[1,0]
	v_mul_f32_e32 v37, v46, v38
	v_mul_f32_e32 v33, v37, v33
	v_mul_f32_e32 v37, v47, v39
	v_mul_f32_e32 v36, v37, v36
	v_mul_f32_e32 v37, 0xbfb8aa3b, v40
	v_exp_f32_e32 v37, v37
	v_mul_f32_e32 v38, 0xbfb8aa3b, v41
	v_exp_f32_e32 v38, v38
	v_cvt_pk_bf16_f32 v33, v33, v36
	v_add_f32_e32 v36, 1.0, v37
	v_rcp_f32_e32 v36, v36
	v_add_f32_e32 v37, 1.0, v38
	v_rcp_f32_e32 v37, v37
	v_pk_mul_f32 v[42:43], v[42:43], v[74:75] op_sel_hi:[1,0]
	v_mul_f32_e32 v34, v40, v34
	v_mul_f32_e32 v34, v34, v36
	v_mul_f32_e32 v35, v41, v35
	v_mul_f32_e32 v36, 0xbfb8aa3b, v42
	v_mul_f32_e32 v35, v35, v37
	v_exp_f32_e32 v36, v36
	v_mul_f32_e32 v37, 0xbfb8aa3b, v43
	v_exp_f32_e32 v37, v37
	v_cvt_pk_bf16_f32 v34, v34, v35
	v_add_f32_e32 v35, 1.0, v36
	v_rcp_f32_e32 v35, v35
	v_add_f32_e32 v36, 1.0, v37
	v_rcp_f32_e32 v36, v36
	v_mul_f32_e32 v37, v42, v48
	v_mul_f32_e32 v35, v37, v35
	v_mul_f32_e32 v37, v43, v49
	v_mul_f32_e32 v36, v37, v36
	v_cvt_pk_bf16_f32 v35, v35, v36
	v_mad_i64_i32 v[36:37], s[20:21], v70, s48, v[112:113]
	v_lshl_add_u64 v[36:37], v[36:37], 0, v[114:115]
	v_pk_mul_f32 v[28:29], v[28:29], v[76:77] op_sel_hi:[1,0]
	global_store_dwordx4 v[36:37], v[32:35], off
	v_pk_mul_f32 v[20:21], v[20:21], v[76:77] op_sel_hi:[1,0]
	v_pk_mul_f32 v[30:31], v[30:31], v[76:77] op_sel_hi:[1,0]
	v_pk_mul_f32 v[32:33], v[18:19], v[76:77] op_sel_hi:[1,0]
	v_mul_f32_e32 v18, 0xbfb8aa3b, v28
	v_exp_f32_e32 v34, v18
	v_mul_f32_e32 v18, 0xbfb8aa3b, v29
	v_exp_f32_e32 v35, v18
	v_pk_mul_f32 v[18:19], v[16:17], v[76:77] op_sel_hi:[1,0]
	v_add_f32_e32 v16, 1.0, v34
	v_rcp_f32_e32 v16, v16
	v_add_f32_e32 v17, 1.0, v35
	v_rcp_f32_e32 v17, v17
	v_mul_f32_e32 v20, v28, v20
	v_mul_f32_e32 v16, v20, v16
	v_mul_f32_e32 v20, v29, v21
	v_mul_f32_e32 v17, v20, v17
	v_mul_f32_e32 v20, 0xbfb8aa3b, v30
	v_exp_f32_e32 v20, v20
	v_mul_f32_e32 v21, 0xbfb8aa3b, v31
	v_exp_f32_e32 v21, v21
	v_cvt_pk_bf16_f32 v16, v16, v17
	v_add_f32_e32 v17, 1.0, v20
	v_rcp_f32_e32 v17, v17
	v_add_f32_e32 v20, 1.0, v21
	v_rcp_f32_e32 v20, v20
	v_pk_mul_f32 v[22:23], v[22:23], v[76:77] op_sel_hi:[1,0]
	v_pk_mul_f32 v[24:25], v[24:25], v[76:77] op_sel_hi:[1,0]
	v_mul_f32_e32 v21, v30, v22
	v_mul_f32_e32 v17, v21, v17
	v_mul_f32_e32 v21, v31, v23
	v_mul_f32_e32 v20, v21, v20
	v_mul_f32_e32 v21, 0xbfb8aa3b, v24
	v_exp_f32_e32 v21, v21
	v_mul_f32_e32 v22, 0xbfb8aa3b, v25
	v_exp_f32_e32 v22, v22
	v_cvt_pk_bf16_f32 v17, v17, v20
	v_add_f32_e32 v20, 1.0, v21
	v_rcp_f32_e32 v20, v20
	v_add_f32_e32 v21, 1.0, v22
	v_rcp_f32_e32 v21, v21
	v_pk_mul_f32 v[26:27], v[26:27], v[76:77] op_sel_hi:[1,0]
	v_mul_f32_e32 v18, v24, v18
	v_mul_f32_e32 v18, v18, v20
	v_mul_f32_e32 v19, v25, v19
	v_mul_f32_e32 v20, 0xbfb8aa3b, v26
	v_mul_f32_e32 v19, v19, v21
	v_exp_f32_e32 v20, v20
	v_mul_f32_e32 v21, 0xbfb8aa3b, v27
	v_exp_f32_e32 v21, v21
	v_cvt_pk_bf16_f32 v18, v18, v19
	v_add_f32_e32 v19, 1.0, v20
	v_rcp_f32_e32 v19, v19
	v_add_f32_e32 v20, 1.0, v21
	v_rcp_f32_e32 v20, v20
	v_mul_f32_e32 v21, v26, v32
	v_mul_f32_e32 v19, v21, v19
	v_mul_f32_e32 v21, v27, v33
	v_mul_f32_e32 v20, v21, v20
	v_cvt_pk_bf16_f32 v19, v19, v20
	v_mad_i64_i32 v[20:21], s[20:21], v66, s48, v[112:113]
	v_lshl_add_u64 v[20:21], v[20:21], 0, v[114:115]
	v_pk_mul_f32 v[12:13], v[12:13], v[68:69] op_sel_hi:[1,0]
	global_store_dwordx4 v[20:21], v[16:19], off
	v_pk_mul_f32 v[4:5], v[4:5], v[68:69] op_sel_hi:[1,0]
	v_pk_mul_f32 v[14:15], v[14:15], v[68:69] op_sel_hi:[1,0]
	v_pk_mul_f32 v[16:17], v[2:3], v[68:69] op_sel_hi:[1,0]
	v_mul_f32_e32 v2, 0xbfb8aa3b, v12
	v_exp_f32_e32 v18, v2
	v_mul_f32_e32 v2, 0xbfb8aa3b, v13
	v_exp_f32_e32 v19, v2
	v_pk_mul_f32 v[2:3], v[0:1], v[68:69] op_sel_hi:[1,0]
	v_add_f32_e32 v0, 1.0, v18
	v_rcp_f32_e32 v0, v0
	v_add_f32_e32 v1, 1.0, v19
	v_rcp_f32_e32 v1, v1
	v_mul_f32_e32 v4, v12, v4
	v_mul_f32_e32 v0, v4, v0
	v_mul_f32_e32 v4, v13, v5
	v_mul_f32_e32 v1, v4, v1
	v_mul_f32_e32 v4, 0xbfb8aa3b, v14
	v_exp_f32_e32 v4, v4
	v_mul_f32_e32 v5, 0xbfb8aa3b, v15
	v_exp_f32_e32 v5, v5
	v_cvt_pk_bf16_f32 v0, v0, v1
	v_add_f32_e32 v1, 1.0, v4
	v_rcp_f32_e32 v1, v1
	v_add_f32_e32 v4, 1.0, v5
	v_rcp_f32_e32 v4, v4
	v_pk_mul_f32 v[6:7], v[6:7], v[68:69] op_sel_hi:[1,0]
	v_pk_mul_f32 v[8:9], v[8:9], v[68:69] op_sel_hi:[1,0]
	v_mul_f32_e32 v5, v14, v6
	v_mul_f32_e32 v1, v5, v1
	v_mul_f32_e32 v5, v15, v7
	v_mul_f32_e32 v4, v5, v4
	v_mul_f32_e32 v5, 0xbfb8aa3b, v8
	v_exp_f32_e32 v5, v5
	v_mul_f32_e32 v6, 0xbfb8aa3b, v9
	v_exp_f32_e32 v6, v6
	v_cvt_pk_bf16_f32 v1, v1, v4
	v_add_f32_e32 v4, 1.0, v5
	v_rcp_f32_e32 v4, v4
	v_add_f32_e32 v5, 1.0, v6
	v_rcp_f32_e32 v5, v5
	v_pk_mul_f32 v[10:11], v[10:11], v[68:69] op_sel_hi:[1,0]
	v_mul_f32_e32 v2, v8, v2
	v_mul_f32_e32 v2, v2, v4
	v_mul_f32_e32 v3, v9, v3
	v_mul_f32_e32 v4, 0xbfb8aa3b, v10
	v_mul_f32_e32 v3, v3, v5
	v_exp_f32_e32 v4, v4
	v_mul_f32_e32 v5, 0xbfb8aa3b, v11
	v_exp_f32_e32 v5, v5
	v_cvt_pk_bf16_f32 v2, v2, v3
	v_add_f32_e32 v3, 1.0, v4
	v_rcp_f32_e32 v3, v3
	v_add_f32_e32 v4, 1.0, v5
	v_rcp_f32_e32 v4, v4
	v_mul_f32_e32 v5, v10, v16
	v_mul_f32_e32 v3, v5, v3
	v_mul_f32_e32 v5, v11, v17
	v_mul_f32_e32 v4, v5, v4
	v_cvt_pk_bf16_f32 v3, v3, v4
	v_mad_i64_i32 v[4:5], s[20:21], v64, s48, v[112:113]
	v_lshl_add_u64 v[4:5], v[4:5], 0, v[114:115]
	global_store_dwordx4 v[4:5], v[0:3], off
	s_cbranch_vccnz .LBB0_2119
	s_andn2_b64 vcc, exec, s[4:5]
	s_cbranch_vccnz .LBB0_2118
	s_barrier
	s_branch .LBB0_2118
